# first load-segment wait of each tile counts the epilogue's guaranteed VMEM ops (vmcnt 22-40 instead of 8) so epilogue stores are not drained at the tile's first barrier
# speedup vs baseline: 1.0138x; 1.0029x over previous
; #define PG8_STAGE(bufoff, gbase, voff) do { _Pragma("unroll") for (int _i = 0; _i < 2; ++_i) \
;         __builtin_amdgcn_global_load_lds((const unsigned*)((const char*)(gbase) + (voff)[_i]), (LAS unsigned*)(lds + (bufoff) + ldsw + _i * 8192), 16, 0, 0); } while (0)
; #define PG8_LDA(dst, b, h) do { _Pragma("unroll") for (int m = 0; m < 4; ++m) _Pragma("unroll") for (int k = 0; k < 2; ++k) dst[m][k] = *(const LAS h16x8*)(lds + PG8_SA(b, h) + aoff + m * 2048 + k * 1024); } while (0)
; #define PG8_LDB(dst, b, h) do { _Pragma("unroll") for (int n = 0; n < 2; ++n) _Pragma("unroll") for (int k = 0; k < 2; ++k) dst[n][k] = *(const LAS h16x8*)(lds + PG8_SB(b, h) + boff + n * 2048 + k * 1024); } while (0)
; #define PG8_MMA(ai, bj, At, Bt_) do { __builtin_amdgcn_s_setprio(1); _Pragma("unroll") for (int m = 0; m < 4; ++m) _Pragma("unroll") for (int n = 0; n < 2; ++n) _Pragma("unroll") for (int k = 0; k < 2; ++k) \
;         acc[ai][bj][m][n] = __builtin_amdgcn_mfma_f32_16x16x32_f16(Bt_[n][k], At[m][k], acc[ai][bj][m][n], 0, 0, 0); __builtin_amdgcn_s_setprio(0); } while (0)
; #define PG8_WAIT_V(n) asm volatile("s_waitcnt vmcnt(" #n ")" ::: "memory")
; #define PG8_WAIT_L(n) asm volatile("s_waitcnt lgkmcnt(" #n ")" ::: "memory")
; #define PG8_BAR __builtin_amdgcn_s_barrier()
; #define PG8_SCHED __builtin_amdgcn_sched_barrier(0)
; template <class Epi, class AMap>
; __device__ __forceinline__ void gemm_phase(LAS unsigned char* lds, const AMap am, const int lda, const h16* Bt, const int ldb, const int M, const int N, const int K, const Epi& E) {
;     ...
;             PG8_LDB(B0, 0, 0); PG8_SCHED; PG8_LDA(At, 0, 0); PG8_STAGE(PG8_SA(1, 1), a1 + hstepA, voffA);
;             PG8_WAIT_L(8); PG8_BAR; PG8_WAIT_L(0); PG8_MMA(0, 0, At, B0); PG8_BAR; PG8_SCHED;
;             PG8_LDB(B1, 0, 1); PG8_STAGE(PG8_SB(0, 0), b2, voffB);
;             PG8_BAR; PG8_WAIT_L(0); PG8_MMA(0, 1, At, B1); PG8_BAR;
;             PG8_LDA(At, 0, 1); PG8_STAGE(PG8_SA(0, 0), a2, voffA);
;             PG8_BAR; PG8_WAIT_L(0); PG8_MMA(1, 0, At, B0); PG8_BAR; PG8_SCHED;
;             PG8_STAGE(PG8_SB(0, 1), b2 + hstepB, voffB);
;             PG8_WAIT_V(6); PG8_BAR; PG8_MMA(1, 1, At, B1); PG8_BAR;
.Lg4p_61:
	s_add_u32 s26, s22, 0x100
	s_addc_u32 s27, s23, 0
	s_add_i32 s51, 0, 0x10000
	v_add_u32_e32 v144, s51, v147
	ds_read_b128 v[140:143], v144
	ds_read_b128 v[150:153], v144 offset:1024
	ds_read_b128 v[154:157], v144 offset:2048
	ds_read_b128 v[158:161], v144 offset:3072
	s_cmpk_eq_i32 s29, 0x52
	s_cselect_b32 s45, s1, s27
	s_cselect_b32 s44, s0, s26
	s_cselect_b32 s43, s41, s21
	s_cselect_b32 s42, s40, s20
	v_lshl_add_u64 v[144:145], s[22:23], 0, v[136:137]
	s_add_i32 m0, s63, 0xc000
	ds_read_b128 v[162:165], v149
	ds_read_b128 v[166:169], v149 offset:1024
	ds_read_b128 v[170:173], v149 offset:2048
	ds_read_b128 v[174:177], v149 offset:3072
	ds_read_b128 v[178:181], v149 offset:4096
	ds_read_b128 v[182:185], v149 offset:5120
	ds_read_b128 v[186:189], v149 offset:6144
	ds_read_b128 v[190:193], v149 offset:7168
	global_load_lds_dwordx4 v[144:145], off
	v_lshl_add_u64 v[144:145], s[22:23], 0, v[138:139]
	s_add_i32 m0, s63, 0xe000
	s_nop 0
	global_load_lds_dwordx4 v[144:145], off
	s_waitcnt lgkmcnt(11)
	s_add_i32 s60, 0, 0x14000
	v_add_u32_e32 v144, s60, v147
	s_add_i32 s22, s51, s48
	ds_read_b128 v[194:197], v144
	ds_read_b128 v[198:201], v144 offset:1024
	ds_read_b128 v[202:205], v144 offset:2048
	ds_read_b128 v[220:223], v144 offset:3072
	s_waitcnt vmcnt(40) lgkmcnt(0)
	s_barrier
	v_mfma_f32_16x16x32_f16 v[126:129], v[140:143], v[162:165], 0
	v_mfma_f32_16x16x32_f16 v[122:125], v[154:157], v[162:165], 0
	v_mfma_f32_16x16x32_f16 v[110:113], v[140:143], v[170:173], 0
	v_mfma_f32_16x16x32_f16 v[106:109], v[154:157], v[170:173], 0
	v_mfma_f32_16x16x32_f16 v[94:97], v[140:143], v[178:181], 0
	v_mfma_f32_16x16x32_f16 v[90:93], v[154:157], v[178:181], 0
	v_mfma_f32_16x16x32_f16 v[78:81], v[140:143], v[186:189], 0
	v_mfma_f32_16x16x32_f16 v[74:77], v[154:157], v[186:189], 0
	v_mfma_f32_16x16x32_f16 v[126:129], v[150:153], v[166:169], v[126:129]
	v_mfma_f32_16x16x32_f16 v[122:125], v[158:161], v[166:169], v[122:125]
	v_mfma_f32_16x16x32_f16 v[110:113], v[150:153], v[174:177], v[110:113]
	v_mfma_f32_16x16x32_f16 v[106:109], v[158:161], v[174:177], v[106:109]
	v_mfma_f32_16x16x32_f16 v[94:97], v[150:153], v[182:185], v[94:97]
	v_mfma_f32_16x16x32_f16 v[90:93], v[158:161], v[182:185], v[90:93]
	v_mfma_f32_16x16x32_f16 v[78:81], v[150:153], v[190:193], v[78:81]
	v_mfma_f32_16x16x32_f16 v[74:77], v[158:161], v[190:193], v[74:77]
	v_mfma_f32_16x16x32_f16 v[118:121], v[194:197], v[162:165], 0
	v_mfma_f32_16x16x32_f16 v[114:117], v[202:205], v[162:165], 0
	v_mfma_f32_16x16x32_f16 v[102:105], v[194:197], v[170:173], 0
	v_mfma_f32_16x16x32_f16 v[98:101], v[202:205], v[170:173], 0
	v_mfma_f32_16x16x32_f16 v[86:89], v[194:197], v[178:181], 0
	v_mfma_f32_16x16x32_f16 v[82:85], v[202:205], v[178:181], 0
	v_mfma_f32_16x16x32_f16 v[70:73], v[194:197], v[186:189], 0
	v_mfma_f32_16x16x32_f16 v[66:69], v[202:205], v[186:189], 0
	v_mfma_f32_16x16x32_f16 v[118:121], v[198:201], v[166:169], v[118:121]
	v_mfma_f32_16x16x32_f16 v[114:117], v[220:223], v[166:169], v[114:117]
	v_mfma_f32_16x16x32_f16 v[102:105], v[198:201], v[174:177], v[102:105]
	v_mfma_f32_16x16x32_f16 v[98:101], v[220:223], v[174:177], v[98:101]
	v_mfma_f32_16x16x32_f16 v[86:89], v[198:201], v[182:185], v[86:89]
	v_mfma_f32_16x16x32_f16 v[82:85], v[220:223], v[182:185], v[82:85]
	v_mfma_f32_16x16x32_f16 v[70:73], v[198:201], v[190:193], v[70:73]
	v_mfma_f32_16x16x32_f16 v[66:69], v[220:223], v[190:193], v[66:69]
	s_barrier
	v_lshl_add_u64 v[144:145], s[42:43], 0, v[0:1]
	s_mov_b32 m0, s22
	v_lshl_add_u64 v[206:207], s[42:43], 0, v[134:135]
	global_load_lds_dwordx4 v[144:145], off
	s_add_i32 m0, s22, 0x2000
	s_nop 0
	global_load_lds_dwordx4 v[206:207], off
	s_mov_b32 m0, s63
	v_lshl_add_u64 v[212:213], s[44:45], 0, v[130:131]
	ds_read_b128 v[162:165], v149 offset:16384
	ds_read_b128 v[166:169], v149 offset:17408
	ds_read_b128 v[170:173], v149 offset:18432
	ds_read_b128 v[174:177], v149 offset:19456
	ds_read_b128 v[178:181], v149 offset:20480
	ds_read_b128 v[182:185], v149 offset:21504
	ds_read_b128 v[186:189], v149 offset:22528
	ds_read_b128 v[190:193], v149 offset:23552
	global_load_lds_dwordx4 v[212:213], off
	v_lshl_add_u64 v[214:215], s[44:45], 0, v[132:133]
	s_mov_b32 m0, s64
	s_nop 0
	global_load_lds_dwordx4 v[214:215], off
	s_add_u32 s22, s42, 0x158000
	s_addc_u32 s23, s43, 0
	s_add_i32 s51, s60, s48
	v_lshl_add_u64 v[232:233], s[22:23], 0, v[0:1]
	s_mov_b32 m0, s51
	s_nop 0
	global_load_lds_dwordx4 v[232:233], off
	v_lshl_add_u64 v[232:233], s[22:23], 0, v[134:135]
	s_add_i32 m0, s51, 0x2000
	s_nop 0
	global_load_lds_dwordx4 v[232:233], off
	s_waitcnt vmcnt(8) lgkmcnt(0)
	s_barrier
; #define PG8_STAGE(bufoff, gbase, voff) do { _Pragma("unroll") for (int _i = 0; _i < 2; ++_i) \
;         __builtin_amdgcn_global_load_lds((const unsigned*)((const char*)(gbase) + (voff)[_i]), (LAS unsigned*)(lds + (bufoff) + ldsw + _i * 8192), 16, 0, 0); } while (0)
; #define PG8_LDA(dst, b, h) do { _Pragma("unroll") for (int m = 0; m < 4; ++m) _Pragma("unroll") for (int k = 0; k < 2; ++k) dst[m][k] = *(const LAS h16x8*)(lds + PG8_SA(b, h) + aoff + m * 2048 + k * 1024); } while (0)
; #define PG8_LDB(dst, b, h) do { _Pragma("unroll") for (int n = 0; n < 2; ++n) _Pragma("unroll") for (int k = 0; k < 2; ++k) dst[n][k] = *(const LAS h16x8*)(lds + PG8_SB(b, h) + boff + n * 2048 + k * 1024); } while (0)
; #define PG8_MMA(ai, bj, At, Bt_) do { __builtin_amdgcn_s_setprio(1); _Pragma("unroll") for (int m = 0; m < 4; ++m) _Pragma("unroll") for (int n = 0; n < 2; ++n) _Pragma("unroll") for (int k = 0; k < 2; ++k) \
;         acc[ai][bj][m][n] = __builtin_amdgcn_mfma_f32_16x16x32_f16(Bt_[n][k], At[m][k], acc[ai][bj][m][n], 0, 0, 0); __builtin_amdgcn_s_setprio(0); } while (0)
; #define PG8_WAIT_V(n) asm volatile("s_waitcnt vmcnt(" #n ")" ::: "memory")
; #define PG8_WAIT_L(n) asm volatile("s_waitcnt lgkmcnt(" #n ")" ::: "memory")
; #define PG8_BAR __builtin_amdgcn_s_barrier()
; #define PG8_SCHED __builtin_amdgcn_sched_barrier(0)
; template <class Epi, class AMap>
; __device__ __forceinline__ void gemm_phase(LAS unsigned char* lds, const AMap am, const int lda, const h16* Bt, const int ldb, const int M, const int N, const int K, const Epi& E) {
;     ...
;             PG8_WAIT_V(6); PG8_BAR; PG8_MMA(1, 1, At, B1); PG8_BAR;
;             PG8_LDB(B0, 1, 0); PG8_SCHED; PG8_LDA(At, 1, 0); PG8_STAGE(PG8_SA(0, 1), a2 + hstepA, voffA);
;             PG8_WAIT_L(8); PG8_BAR; PG8_WAIT_L(0); PG8_MMA(0, 0, At, B0); PG8_BAR; PG8_SCHED;
;             PG8_LDB(B1, 1, 1); PG8_STAGE(PG8_SB(1, 0), b3, voffB);
;             PG8_BAR; PG8_WAIT_L(0); PG8_MMA(0, 1, At, B1); PG8_BAR;
	v_mfma_f32_16x16x32_f16 v[62:65], v[140:143], v[162:165], 0
	v_mfma_f32_16x16x32_f16 v[58:61], v[154:157], v[162:165], 0
	v_mfma_f32_16x16x32_f16 v[46:49], v[140:143], v[170:173], 0
	v_mfma_f32_16x16x32_f16 v[42:45], v[154:157], v[170:173], 0
	v_mfma_f32_16x16x32_f16 v[30:33], v[140:143], v[178:181], 0
	v_mfma_f32_16x16x32_f16 v[26:29], v[154:157], v[178:181], 0
	v_mfma_f32_16x16x32_f16 v[14:17], v[140:143], v[186:189], 0
	v_mfma_f32_16x16x32_f16 v[10:13], v[154:157], v[186:189], 0
	v_mfma_f32_16x16x32_f16 v[62:65], v[150:153], v[166:169], v[62:65]
	v_mfma_f32_16x16x32_f16 v[58:61], v[158:161], v[166:169], v[58:61]
	v_mfma_f32_16x16x32_f16 v[46:49], v[150:153], v[174:177], v[46:49]
	v_mfma_f32_16x16x32_f16 v[42:45], v[158:161], v[174:177], v[42:45]
	v_mfma_f32_16x16x32_f16 v[30:33], v[150:153], v[182:185], v[30:33]
	v_mfma_f32_16x16x32_f16 v[26:29], v[158:161], v[182:185], v[26:29]
	v_mfma_f32_16x16x32_f16 v[14:17], v[150:153], v[190:193], v[14:17]
	v_mfma_f32_16x16x32_f16 v[10:13], v[158:161], v[190:193], v[10:13]
	v_mfma_f32_16x16x32_f16 v[54:57], v[194:197], v[162:165], 0
	v_mfma_f32_16x16x32_f16 v[50:53], v[202:205], v[162:165], 0
	v_mfma_f32_16x16x32_f16 v[38:41], v[194:197], v[170:173], 0
	v_mfma_f32_16x16x32_f16 v[34:37], v[202:205], v[170:173], 0
	v_mfma_f32_16x16x32_f16 v[22:25], v[194:197], v[178:181], 0
	v_mfma_f32_16x16x32_f16 v[18:21], v[202:205], v[178:181], 0
	v_mfma_f32_16x16x32_f16 v[6:9], v[194:197], v[186:189], 0
	v_mfma_f32_16x16x32_f16 v[2:5], v[202:205], v[186:189], 0
	v_mfma_f32_16x16x32_f16 v[54:57], v[198:201], v[166:169], v[54:57]
	v_mfma_f32_16x16x32_f16 v[50:53], v[220:223], v[166:169], v[50:53]
	v_mfma_f32_16x16x32_f16 v[38:41], v[198:201], v[174:177], v[38:41]
	v_mfma_f32_16x16x32_f16 v[34:37], v[220:223], v[174:177], v[34:37]
	v_mfma_f32_16x16x32_f16 v[22:25], v[198:201], v[182:185], v[22:25]
	v_mfma_f32_16x16x32_f16 v[18:21], v[220:223], v[182:185], v[18:21]
	v_mfma_f32_16x16x32_f16 v[6:9], v[198:201], v[190:193], v[6:9]
	v_mfma_f32_16x16x32_f16 v[2:5], v[220:223], v[190:193], v[2:5]
	s_barrier
	s_add_i32 s51, 0, 0x18000
	v_add_u32_e32 v234, s51, v147
	ds_read_b128 v[140:143], v234
	ds_read_b128 v[150:153], v234 offset:1024
	ds_read_b128 v[154:157], v234 offset:2048
	ds_read_b128 v[158:161], v234 offset:3072
	s_add_u32 s22, s44, 0x158000
	s_addc_u32 s23, s45, 0
	s_mov_b32 m0, s65
	v_lshl_add_u64 v[232:233], s[22:23], 0, v[130:131]
	ds_read_b128 v[162:165], v149 offset:32768
	ds_read_b128 v[166:169], v149 offset:33792
	ds_read_b128 v[170:173], v149 offset:34816
	ds_read_b128 v[174:177], v149 offset:35840
	ds_read_b128 v[178:181], v149 offset:36864
	ds_read_b128 v[182:185], v149 offset:37888
	ds_read_b128 v[186:189], v149 offset:38912
	ds_read_b128 v[190:193], v149 offset:39936
	global_load_lds_dwordx4 v[232:233], off
	v_lshl_add_u64 v[232:233], s[22:23], 0, v[132:133]
	s_mov_b32 m0, s68
	s_nop 0
	global_load_lds_dwordx4 v[232:233], off
	s_waitcnt lgkmcnt(11)
	s_add_i32 s44, 0, 0x1c000
	s_add_i32 s22, s51, s48
	v_add_u32_e32 v216, s44, v147
	v_lshl_add_u64 v[144:145], v[144:145], 0, s[92:93]
	s_mov_b32 m0, s22
	ds_read_b128 v[194:197], v216
	ds_read_b128 v[198:201], v216 offset:1024
	ds_read_b128 v[202:205], v216 offset:2048
	ds_read_b128 v[220:223], v216 offset:3072
	s_waitcnt vmcnt(8) lgkmcnt(0)
	s_barrier
	v_mfma_f32_16x16x32_f16 v[126:129], v[140:143], v[162:165], v[126:129]
	v_mfma_f32_16x16x32_f16 v[122:125], v[154:157], v[162:165], v[122:125]
	v_mfma_f32_16x16x32_f16 v[110:113], v[140:143], v[170:173], v[110:113]
	v_mfma_f32_16x16x32_f16 v[106:109], v[154:157], v[170:173], v[106:109]
	v_mfma_f32_16x16x32_f16 v[94:97], v[140:143], v[178:181], v[94:97]
	v_mfma_f32_16x16x32_f16 v[90:93], v[154:157], v[178:181], v[90:93]
	v_mfma_f32_16x16x32_f16 v[78:81], v[140:143], v[186:189], v[78:81]
	v_mfma_f32_16x16x32_f16 v[74:77], v[154:157], v[186:189], v[74:77]
	v_mfma_f32_16x16x32_f16 v[126:129], v[150:153], v[166:169], v[126:129]
	v_mfma_f32_16x16x32_f16 v[122:125], v[158:161], v[166:169], v[122:125]
	v_mfma_f32_16x16x32_f16 v[110:113], v[150:153], v[174:177], v[110:113]
	v_mfma_f32_16x16x32_f16 v[106:109], v[158:161], v[174:177], v[106:109]
	v_mfma_f32_16x16x32_f16 v[94:97], v[150:153], v[182:185], v[94:97]
	v_mfma_f32_16x16x32_f16 v[90:93], v[158:161], v[182:185], v[90:93]
	v_mfma_f32_16x16x32_f16 v[78:81], v[150:153], v[190:193], v[78:81]
	v_mfma_f32_16x16x32_f16 v[74:77], v[158:161], v[190:193], v[74:77]
	v_mfma_f32_16x16x32_f16 v[118:121], v[194:197], v[162:165], v[118:121]
	v_mfma_f32_16x16x32_f16 v[114:117], v[202:205], v[162:165], v[114:117]
	v_mfma_f32_16x16x32_f16 v[102:105], v[194:197], v[170:173], v[102:105]
	v_mfma_f32_16x16x32_f16 v[98:101], v[202:205], v[170:173], v[98:101]
	v_mfma_f32_16x16x32_f16 v[86:89], v[194:197], v[178:181], v[86:89]
	v_mfma_f32_16x16x32_f16 v[82:85], v[202:205], v[178:181], v[82:85]
	v_mfma_f32_16x16x32_f16 v[70:73], v[194:197], v[186:189], v[70:73]
	v_mfma_f32_16x16x32_f16 v[66:69], v[202:205], v[186:189], v[66:69]
	v_mfma_f32_16x16x32_f16 v[118:121], v[198:201], v[166:169], v[118:121]
	v_mfma_f32_16x16x32_f16 v[114:117], v[220:223], v[166:169], v[114:117]
	v_mfma_f32_16x16x32_f16 v[102:105], v[198:201], v[174:177], v[102:105]
	v_mfma_f32_16x16x32_f16 v[98:101], v[220:223], v[174:177], v[98:101]
	v_mfma_f32_16x16x32_f16 v[86:89], v[198:201], v[182:185], v[86:89]
	v_mfma_f32_16x16x32_f16 v[82:85], v[220:223], v[182:185], v[82:85]
	v_mfma_f32_16x16x32_f16 v[70:73], v[198:201], v[190:193], v[70:73]
	v_mfma_f32_16x16x32_f16 v[66:69], v[220:223], v[190:193], v[66:69]
	s_barrier
; #define PG8_STAGE(bufoff, gbase, voff) do { _Pragma("unroll") for (int _i = 0; _i < 2; ++_i) \
;         __builtin_amdgcn_global_load_lds((const unsigned*)((const char*)(gbase) + (voff)[_i]), (LAS unsigned*)(lds + (bufoff) + ldsw + _i * 8192), 16, 0, 0); } while (0)
; #define PG8_LDA(dst, b, h) do { _Pragma("unroll") for (int m = 0; m < 4; ++m) _Pragma("unroll") for (int k = 0; k < 2; ++k) dst[m][k] = *(const LAS h16x8*)(lds + PG8_SA(b, h) + aoff + m * 2048 + k * 1024); } while (0)
; #define PG8_MMA(ai, bj, At, Bt_) do { __builtin_amdgcn_s_setprio(1); _Pragma("unroll") for (int m = 0; m < 4; ++m) _Pragma("unroll") for (int n = 0; n < 2; ++n) _Pragma("unroll") for (int k = 0; k < 2; ++k) \
;         acc[ai][bj][m][n] = __builtin_amdgcn_mfma_f32_16x16x32_f16(Bt_[n][k], At[m][k], acc[ai][bj][m][n], 0, 0, 0); __builtin_amdgcn_s_setprio(0); } while (0)
; #define PG8_WAIT_V(n) asm volatile("s_waitcnt vmcnt(" #n ")" ::: "memory")
; #define PG8_WAIT_L(n) asm volatile("s_waitcnt lgkmcnt(" #n ")" ::: "memory")
; #define PG8_BAR __builtin_amdgcn_s_barrier()
; #define PG8_SCHED __builtin_amdgcn_sched_barrier(0)
; template <class Epi, class AMap>
; __device__ __forceinline__ void gemm_phase(LAS unsigned char* lds, const AMap am, const int lda, const h16* Bt, const int ldb, const int M, const int N, const int K, const Epi& E) {
;     ...
;             PG8_LDA(At, 1, 1); PG8_STAGE(PG8_SA(1, 0), a3, voffA);
;             PG8_BAR; PG8_WAIT_L(0); PG8_MMA(1, 0, At, B0); PG8_BAR; PG8_SCHED;
;             PG8_STAGE(PG8_SB(1, 1), b3 + hstepB, voffB);
;             PG8_WAIT_V(6); PG8_BAR; PG8_MMA(1, 1, At, B1); PG8_BAR;
	global_load_lds_dwordx4 v[144:145], off
	v_lshl_add_u64 v[144:145], v[206:207], 0, s[92:93]
	s_add_i32 m0, s22, 0x2000
	s_nop 0
	global_load_lds_dwordx4 v[144:145], off
	s_mov_b32 m0, s69
	v_lshl_add_u64 v[144:145], v[212:213], 0, s[92:93]
	ds_read_b128 v[162:165], v149 offset:49152
	ds_read_b128 v[166:169], v149 offset:50176
	ds_read_b128 v[170:173], v149 offset:51200
	ds_read_b128 v[174:177], v149 offset:52224
	ds_read_b128 v[178:181], v149 offset:53248
	ds_read_b128 v[182:185], v149 offset:54272
	ds_read_b128 v[186:189], v149 offset:55296
	ds_read_b128 v[190:193], v149 offset:56320
	global_load_lds_dwordx4 v[144:145], off
	v_lshl_add_u64 v[144:145], v[214:215], 0, s[92:93]
	s_mov_b32 m0, s70
	s_nop 0
	global_load_lds_dwordx4 v[144:145], off
	s_add_u32 s22, s42, 0x158080
	s_addc_u32 s23, s43, 0
	s_add_i32 s42, s44, s48
	v_lshl_add_u64 v[232:233], s[22:23], 0, v[0:1]
	s_mov_b32 m0, s42
	s_nop 0
	global_load_lds_dwordx4 v[232:233], off
	v_lshl_add_u64 v[232:233], s[22:23], 0, v[134:135]
	s_add_i32 m0, s42, 0x2000
	s_nop 0
	global_load_lds_dwordx4 v[232:233], off
	s_add_i32 s29, s29, 2
	s_add_u32 s20, s20, 0x100
	s_addc_u32 s21, s21, 0
	s_cmpk_gt_u32 s29, 0x53
	s_mov_b64 s[22:23], s[26:27]
	s_waitcnt vmcnt(8) lgkmcnt(0)
	s_barrier
	v_mfma_f32_16x16x32_f16 v[62:65], v[140:143], v[162:165], v[62:65]
	v_mfma_f32_16x16x32_f16 v[58:61], v[154:157], v[162:165], v[58:61]
	v_mfma_f32_16x16x32_f16 v[46:49], v[140:143], v[170:173], v[46:49]
	v_mfma_f32_16x16x32_f16 v[42:45], v[154:157], v[170:173], v[42:45]
	v_mfma_f32_16x16x32_f16 v[30:33], v[140:143], v[178:181], v[30:33]
	v_mfma_f32_16x16x32_f16 v[26:29], v[154:157], v[178:181], v[26:29]
	v_mfma_f32_16x16x32_f16 v[14:17], v[140:143], v[186:189], v[14:17]
	v_mfma_f32_16x16x32_f16 v[10:13], v[154:157], v[186:189], v[10:13]
	v_mfma_f32_16x16x32_f16 v[62:65], v[150:153], v[166:169], v[62:65]
	v_mfma_f32_16x16x32_f16 v[58:61], v[158:161], v[166:169], v[58:61]
	v_mfma_f32_16x16x32_f16 v[46:49], v[150:153], v[174:177], v[46:49]
	v_mfma_f32_16x16x32_f16 v[42:45], v[158:161], v[174:177], v[42:45]
	v_mfma_f32_16x16x32_f16 v[30:33], v[150:153], v[182:185], v[30:33]
	v_mfma_f32_16x16x32_f16 v[26:29], v[158:161], v[182:185], v[26:29]
	v_mfma_f32_16x16x32_f16 v[14:17], v[150:153], v[190:193], v[14:17]
	v_mfma_f32_16x16x32_f16 v[10:13], v[158:161], v[190:193], v[10:13]
	v_mfma_f32_16x16x32_f16 v[54:57], v[194:197], v[162:165], v[54:57]
	v_mfma_f32_16x16x32_f16 v[50:53], v[202:205], v[162:165], v[50:53]
	v_mfma_f32_16x16x32_f16 v[38:41], v[194:197], v[170:173], v[38:41]
	v_mfma_f32_16x16x32_f16 v[34:37], v[202:205], v[170:173], v[34:37]
	v_mfma_f32_16x16x32_f16 v[22:25], v[194:197], v[178:181], v[22:25]
	v_mfma_f32_16x16x32_f16 v[18:21], v[202:205], v[178:181], v[18:21]
	v_mfma_f32_16x16x32_f16 v[6:9], v[194:197], v[186:189], v[6:9]
	v_mfma_f32_16x16x32_f16 v[2:5], v[202:205], v[186:189], v[2:5]
	v_mfma_f32_16x16x32_f16 v[54:57], v[198:201], v[166:169], v[54:57]
	v_mfma_f32_16x16x32_f16 v[50:53], v[220:223], v[166:169], v[50:53]
	v_mfma_f32_16x16x32_f16 v[38:41], v[198:201], v[174:177], v[38:41]
	v_mfma_f32_16x16x32_f16 v[34:37], v[220:223], v[174:177], v[34:37]
	v_mfma_f32_16x16x32_f16 v[22:25], v[198:201], v[182:185], v[22:25]
	v_mfma_f32_16x16x32_f16 v[18:21], v[220:223], v[182:185], v[18:21]
	v_mfma_f32_16x16x32_f16 v[6:9], v[198:201], v[190:193], v[6:9]
	v_mfma_f32_16x16x32_f16 v[2:5], v[220:223], v[190:193], v[2:5]
	s_barrier
	s_cbranch_scc1 .Lg4x_61

; #define PG8_STAGE(bufoff, gbase, voff) do { _Pragma("unroll") for (int _i = 0; _i < 2; ++_i) \
;         __builtin_amdgcn_global_load_lds((const unsigned*)((const char*)(gbase) + (voff)[_i]), (LAS unsigned*)(lds + (bufoff) + ldsw + _i * 8192), 16, 0, 0); } while (0)
; #define PG8_LDA(dst, b, h) do { _Pragma("unroll") for (int m = 0; m < 4; ++m) _Pragma("unroll") for (int k = 0; k < 2; ++k) dst[m][k] = *(const LAS h16x8*)(lds + PG8_SA(b, h) + aoff + m * 2048 + k * 1024); } while (0)
; #define PG8_LDB(dst, b, h) do { _Pragma("unroll") for (int n = 0; n < 2; ++n) _Pragma("unroll") for (int k = 0; k < 2; ++k) dst[n][k] = *(const LAS h16x8*)(lds + PG8_SB(b, h) + boff + n * 2048 + k * 1024); } while (0)
; #define PG8_MMA(ai, bj, At, Bt_) do { __builtin_amdgcn_s_setprio(1); _Pragma("unroll") for (int m = 0; m < 4; ++m) _Pragma("unroll") for (int n = 0; n < 2; ++n) _Pragma("unroll") for (int k = 0; k < 2; ++k) \
;         acc[ai][bj][m][n] = __builtin_amdgcn_mfma_f32_16x16x32_f16(Bt_[n][k], At[m][k], acc[ai][bj][m][n], 0, 0, 0); __builtin_amdgcn_s_setprio(0); } while (0)
; #define PG8_WAIT_V(n) asm volatile("s_waitcnt vmcnt(" #n ")" ::: "memory")
; #define PG8_WAIT_L(n) asm volatile("s_waitcnt lgkmcnt(" #n ")" ::: "memory")
; #define PG8_BAR __builtin_amdgcn_s_barrier()
; #define PG8_SCHED __builtin_amdgcn_sched_barrier(0)
; template <class Epi, class AMap>
; __device__ __forceinline__ void gemm_phase(LAS unsigned char* lds, const AMap am, const int lda, const h16* Bt, const int ldb, const int M, const int N, const int K, const Epi& E) {
;     ...
;             PG8_LDB(B0, 0, 0); PG8_SCHED; PG8_LDA(At, 0, 0); PG8_STAGE(PG8_SA(1, 1), a1 + hstepA, voffA);
;             PG8_WAIT_L(8); PG8_BAR; PG8_WAIT_L(0); PG8_MMA(0, 0, At, B0); PG8_BAR; PG8_SCHED;
;             PG8_LDB(B1, 0, 1); PG8_STAGE(PG8_SB(0, 0), b2, voffB);
;             PG8_BAR; PG8_WAIT_L(0); PG8_MMA(0, 1, At, B1); PG8_BAR;
;             PG8_LDA(At, 0, 1); PG8_STAGE(PG8_SA(0, 0), a2, voffA);
;             PG8_BAR; PG8_WAIT_L(0); PG8_MMA(1, 0, At, B0); PG8_BAR; PG8_SCHED;
;             PG8_STAGE(PG8_SB(0, 1), b2 + hstepB, voffB);
;             PG8_WAIT_V(6); PG8_BAR; PG8_MMA(1, 1, At, B1); PG8_BAR;
.Lg4p_92:
	s_add_u32 s0, vcc_lo, 0xfff80080
	s_addc_u32 s1, vcc_hi, -1
	s_add_i32 s67, 0, 0x10000
	v_add_u32_e32 v226, s67, v169
	ds_read_b128 v[66:69], v226
	ds_read_b128 v[70:73], v226 offset:1024
	ds_read_b128 v[74:77], v226 offset:2048
	ds_read_b128 v[78:81], v226 offset:3072
	s_cmp_eq_u32 s60, 28
	s_cselect_b32 s27, s69, s1
	s_cselect_b32 s26, s29, s0
	s_cselect_b32 s49, s73, s66
	s_cselect_b32 s48, s20, s21
	v_lshl_add_u64 v[192:193], vcc, 0, v[172:173]
	s_add_i32 m0, s81, 0xc000
	ds_read_b128 v[90:93], v195
	ds_read_b128 v[94:97], v195 offset:1024
	ds_read_b128 v[98:101], v195 offset:2048
	ds_read_b128 v[102:105], v195 offset:3072
	ds_read_b128 v[176:179], v195 offset:4096
	ds_read_b128 v[180:183], v195 offset:5120
	ds_read_b128 v[184:187], v195 offset:6144
	ds_read_b128 v[188:191], v195 offset:7168
	global_load_lds_dwordx4 v[192:193], off
	v_lshl_add_u64 v[192:193], vcc, 0, v[174:175]
	s_add_i32 m0, s81, 0xe000
	s_nop 0
	global_load_lds_dwordx4 v[192:193], off
	s_waitcnt lgkmcnt(11)
	s_add_i32 s65, 0, 0x14000
	v_add_u32_e32 v192, s65, v169
	s_add_i32 s0, s67, s64
	ds_read_b128 v[196:199], v192
	ds_read_b128 v[200:203], v192 offset:1024
	ds_read_b128 v[204:207], v192 offset:2048
	ds_read_b128 v[220:223], v192 offset:3072
	s_waitcnt vmcnt(22) lgkmcnt(0)
	s_barrier
	v_mfma_f32_16x16x32_f16 v[158:161], v[66:69], v[90:93], 0
	v_mfma_f32_16x16x32_f16 v[154:157], v[74:77], v[90:93], 0
	v_mfma_f32_16x16x32_f16 v[142:145], v[66:69], v[98:101], 0
	v_mfma_f32_16x16x32_f16 v[134:137], v[74:77], v[98:101], 0
	v_mfma_f32_16x16x32_f16 v[126:129], v[66:69], v[176:179], 0
	v_mfma_f32_16x16x32_f16 v[118:121], v[74:77], v[176:179], 0
	v_mfma_f32_16x16x32_f16 v[110:113], v[66:69], v[184:187], 0
	v_mfma_f32_16x16x32_f16 v[106:109], v[74:77], v[184:187], 0
	v_mfma_f32_16x16x32_f16 v[158:161], v[70:73], v[94:97], v[158:161]
	v_mfma_f32_16x16x32_f16 v[154:157], v[78:81], v[94:97], v[154:157]
	v_mfma_f32_16x16x32_f16 v[142:145], v[70:73], v[102:105], v[142:145]
	v_mfma_f32_16x16x32_f16 v[134:137], v[78:81], v[102:105], v[134:137]
	v_mfma_f32_16x16x32_f16 v[126:129], v[70:73], v[180:183], v[126:129]
	v_mfma_f32_16x16x32_f16 v[118:121], v[78:81], v[180:183], v[118:121]
	v_mfma_f32_16x16x32_f16 v[110:113], v[70:73], v[188:191], v[110:113]
	v_mfma_f32_16x16x32_f16 v[106:109], v[78:81], v[188:191], v[106:109]
	v_mfma_f32_16x16x32_f16 v[150:153], v[196:199], v[90:93], 0
	v_mfma_f32_16x16x32_f16 v[146:149], v[204:207], v[90:93], 0
	v_mfma_f32_16x16x32_f16 v[150:153], v[200:203], v[94:97], v[150:153]
	v_mfma_f32_16x16x32_f16 v[146:149], v[220:223], v[94:97], v[146:149]
	v_mfma_f32_16x16x32_f16 v[138:141], v[196:199], v[98:101], 0
	v_mfma_f32_16x16x32_f16 v[130:133], v[204:207], v[98:101], 0
	v_mfma_f32_16x16x32_f16 v[114:117], v[204:207], v[176:179], 0
	v_mfma_f32_16x16x32_f16 v[86:89], v[196:199], v[184:187], 0
	v_mfma_f32_16x16x32_f16 v[82:85], v[204:207], v[184:187], 0
	v_mfma_f32_16x16x32_f16 v[138:141], v[200:203], v[102:105], v[138:141]
	v_mfma_f32_16x16x32_f16 v[130:133], v[220:223], v[102:105], v[130:133]
	v_mfma_f32_16x16x32_f16 v[122:125], v[196:199], v[176:179], 0
	v_mfma_f32_16x16x32_f16 v[114:117], v[220:223], v[180:183], v[114:117]
	v_mfma_f32_16x16x32_f16 v[86:89], v[200:203], v[188:191], v[86:89]
	v_mfma_f32_16x16x32_f16 v[82:85], v[220:223], v[188:191], v[82:85]
	v_mfma_f32_16x16x32_f16 v[122:125], v[200:203], v[180:183], v[122:125]
	s_barrier
	v_lshl_add_u64 v[192:193], s[48:49], 0, v[0:1]
	s_mov_b32 m0, s0
	v_lshl_add_u64 v[212:213], s[48:49], 0, v[162:163]
	global_load_lds_dwordx4 v[192:193], off
	s_add_i32 m0, s0, 0x2000
	s_nop 0
	global_load_lds_dwordx4 v[212:213], off
	s_mov_b32 m0, s81
	v_lshl_add_u64 v[214:215], s[26:27], 0, v[166:167]
	ds_read_b128 v[90:93], v195 offset:16384
	ds_read_b128 v[94:97], v195 offset:17408
	ds_read_b128 v[98:101], v195 offset:18432
	ds_read_b128 v[102:105], v195 offset:19456
	ds_read_b128 v[176:179], v195 offset:20480
	ds_read_b128 v[180:183], v195 offset:21504
	ds_read_b128 v[184:187], v195 offset:22528
	ds_read_b128 v[188:191], v195 offset:23552
	global_load_lds_dwordx4 v[214:215], off
	v_lshl_add_u64 v[216:217], s[26:27], 0, v[164:165]
	s_mov_b32 m0, s82
	s_nop 0
	global_load_lds_dwordx4 v[216:217], off
	s_add_u32 s0, s48, 0x80000
	s_addc_u32 s1, s49, 0
	s_add_i32 s65, s65, s64
	v_lshl_add_u64 v[224:225], s[0:1], 0, v[0:1]
	s_mov_b32 m0, s65
	s_nop 0
	global_load_lds_dwordx4 v[224:225], off
	v_lshl_add_u64 v[224:225], s[0:1], 0, v[162:163]
	s_add_i32 m0, s65, 0x2000
	s_nop 0
	global_load_lds_dwordx4 v[224:225], off
	s_waitcnt vmcnt(8) lgkmcnt(0)
	s_barrier
	v_mfma_f32_16x16x32_f16 v[62:65], v[66:69], v[90:93], 0
	v_mfma_f32_16x16x32_f16 v[58:61], v[74:77], v[90:93], 0
	v_mfma_f32_16x16x32_f16 v[46:49], v[66:69], v[98:101], 0
	v_mfma_f32_16x16x32_f16 v[38:41], v[74:77], v[98:101], 0
	v_mfma_f32_16x16x32_f16 v[30:33], v[66:69], v[176:179], 0
	v_mfma_f32_16x16x32_f16 v[22:25], v[74:77], v[176:179], 0
	v_mfma_f32_16x16x32_f16 v[14:17], v[66:69], v[184:187], 0
	v_mfma_f32_16x16x32_f16 v[10:13], v[74:77], v[184:187], 0
	v_mfma_f32_16x16x32_f16 v[62:65], v[70:73], v[94:97], v[62:65]
	v_mfma_f32_16x16x32_f16 v[58:61], v[78:81], v[94:97], v[58:61]
	v_mfma_f32_16x16x32_f16 v[46:49], v[70:73], v[102:105], v[46:49]
	v_mfma_f32_16x16x32_f16 v[38:41], v[78:81], v[102:105], v[38:41]
	v_mfma_f32_16x16x32_f16 v[30:33], v[70:73], v[180:183], v[30:33]
	v_mfma_f32_16x16x32_f16 v[22:25], v[78:81], v[180:183], v[22:25]
	v_mfma_f32_16x16x32_f16 v[14:17], v[70:73], v[188:191], v[14:17]
	v_mfma_f32_16x16x32_f16 v[10:13], v[78:81], v[188:191], v[10:13]
	v_mfma_f32_16x16x32_f16 v[54:57], v[196:199], v[90:93], 0
	v_mfma_f32_16x16x32_f16 v[50:53], v[204:207], v[90:93], 0
	v_mfma_f32_16x16x32_f16 v[42:45], v[196:199], v[98:101], 0
	v_mfma_f32_16x16x32_f16 v[34:37], v[204:207], v[98:101], 0
	v_mfma_f32_16x16x32_f16 v[26:29], v[196:199], v[176:179], 0
	v_mfma_f32_16x16x32_f16 v[18:21], v[204:207], v[176:179], 0
	v_mfma_f32_16x16x32_f16 v[6:9], v[196:199], v[184:187], 0
	v_mfma_f32_16x16x32_f16 v[2:5], v[204:207], v[184:187], 0
	v_mfma_f32_16x16x32_f16 v[54:57], v[200:203], v[94:97], v[54:57]
	v_mfma_f32_16x16x32_f16 v[50:53], v[220:223], v[94:97], v[50:53]
	v_mfma_f32_16x16x32_f16 v[42:45], v[200:203], v[102:105], v[42:45]
	v_mfma_f32_16x16x32_f16 v[34:37], v[220:223], v[102:105], v[34:37]
	v_mfma_f32_16x16x32_f16 v[26:29], v[200:203], v[180:183], v[26:29]
	v_mfma_f32_16x16x32_f16 v[18:21], v[220:223], v[180:183], v[18:21]
	v_mfma_f32_16x16x32_f16 v[6:9], v[200:203], v[188:191], v[6:9]
	v_mfma_f32_16x16x32_f16 v[2:5], v[220:223], v[188:191], v[2:5]
	s_barrier
; #define PG8_STAGE(bufoff, gbase, voff) do { _Pragma("unroll") for (int _i = 0; _i < 2; ++_i) \
;         __builtin_amdgcn_global_load_lds((const unsigned*)((const char*)(gbase) + (voff)[_i]), (LAS unsigned*)(lds + (bufoff) + ldsw + _i * 8192), 16, 0, 0); } while (0)
; #define PG8_LDA(dst, b, h) do { _Pragma("unroll") for (int m = 0; m < 4; ++m) _Pragma("unroll") for (int k = 0; k < 2; ++k) dst[m][k] = *(const LAS h16x8*)(lds + PG8_SA(b, h) + aoff + m * 2048 + k * 1024); } while (0)
; #define PG8_LDB(dst, b, h) do { _Pragma("unroll") for (int n = 0; n < 2; ++n) _Pragma("unroll") for (int k = 0; k < 2; ++k) dst[n][k] = *(const LAS h16x8*)(lds + PG8_SB(b, h) + boff + n * 2048 + k * 1024); } while (0)
; #define PG8_MMA(ai, bj, At, Bt_) do { __builtin_amdgcn_s_setprio(1); _Pragma("unroll") for (int m = 0; m < 4; ++m) _Pragma("unroll") for (int n = 0; n < 2; ++n) _Pragma("unroll") for (int k = 0; k < 2; ++k) \
;         acc[ai][bj][m][n] = __builtin_amdgcn_mfma_f32_16x16x32_f16(Bt_[n][k], At[m][k], acc[ai][bj][m][n], 0, 0, 0); __builtin_amdgcn_s_setprio(0); } while (0)
; #define PG8_WAIT_V(n) asm volatile("s_waitcnt vmcnt(" #n ")" ::: "memory")
; #define PG8_WAIT_L(n) asm volatile("s_waitcnt lgkmcnt(" #n ")" ::: "memory")
; #define PG8_BAR __builtin_amdgcn_s_barrier()
; #define PG8_SCHED __builtin_amdgcn_sched_barrier(0)
; template <class Epi, class AMap>
; __device__ __forceinline__ void gemm_phase(LAS unsigned char* lds, const AMap am, const int lda, const h16* Bt, const int ldb, const int M, const int N, const int K, const Epi& E) {
;     ...
;             PG8_WAIT_V(6); PG8_BAR; PG8_MMA(1, 1, At, B1); PG8_BAR;
;             PG8_LDB(B0, 1, 0); PG8_SCHED; PG8_LDA(At, 1, 0); PG8_STAGE(PG8_SA(0, 1), a2 + hstepA, voffA);
;             PG8_WAIT_L(8); PG8_BAR; PG8_WAIT_L(0); PG8_MMA(0, 0, At, B0); PG8_BAR; PG8_SCHED;
;             PG8_LDB(B1, 1, 1); PG8_STAGE(PG8_SB(1, 0), b3, voffB);
;             PG8_BAR; PG8_WAIT_L(0); PG8_MMA(0, 1, At, B1); PG8_BAR;
;             PG8_LDA(At, 1, 1); PG8_STAGE(PG8_SA(1, 0), a3, voffA);
;             PG8_BAR; PG8_WAIT_L(0); PG8_MMA(1, 0, At, B0); PG8_BAR; PG8_SCHED;
;             PG8_STAGE(PG8_SB(1, 1), b3 + hstepB, voffB);
;             PG8_WAIT_V(6); PG8_BAR; PG8_MMA(1, 1, At, B1); PG8_BAR;
	s_add_i32 s65, 0, 0x18000
	v_add_u32_e32 v226, s65, v169
	ds_read_b128 v[66:69], v226
	ds_read_b128 v[70:73], v226 offset:1024
	ds_read_b128 v[74:77], v226 offset:2048
	ds_read_b128 v[78:81], v226 offset:3072
	s_add_u32 s0, s26, 0x80000
	s_addc_u32 s1, s27, 0
	s_mov_b32 m0, s83
	v_lshl_add_u64 v[224:225], s[0:1], 0, v[166:167]
	ds_read_b128 v[90:93], v195 offset:32768
	ds_read_b128 v[94:97], v195 offset:33792
	ds_read_b128 v[98:101], v195 offset:34816
	ds_read_b128 v[102:105], v195 offset:35840
	ds_read_b128 v[176:179], v195 offset:36864
	ds_read_b128 v[180:183], v195 offset:37888
	ds_read_b128 v[184:187], v195 offset:38912
	ds_read_b128 v[188:191], v195 offset:39936
	global_load_lds_dwordx4 v[224:225], off
	v_lshl_add_u64 v[224:225], s[0:1], 0, v[164:165]
	s_mov_b32 m0, s50
	s_nop 0
	global_load_lds_dwordx4 v[224:225], off
	s_waitcnt lgkmcnt(11)
	s_add_i32 s26, 0, 0x1c000
	v_add_u32_e32 v226, s26, v169
	s_add_i32 s0, s65, s64
	ds_read_b128 v[196:199], v226
	ds_read_b128 v[200:203], v226 offset:1024
	ds_read_b128 v[204:207], v226 offset:2048
	ds_read_b128 v[220:223], v226 offset:3072
	s_waitcnt vmcnt(8) lgkmcnt(0)
	s_barrier
	v_mfma_f32_16x16x32_f16 v[158:161], v[66:69], v[90:93], v[158:161]
	v_mfma_f32_16x16x32_f16 v[158:161], v[70:73], v[94:97], v[158:161]
	v_mfma_f32_16x16x32_f16 v[154:157], v[74:77], v[90:93], v[154:157]
	v_mfma_f32_16x16x32_f16 v[154:157], v[78:81], v[94:97], v[154:157]
	v_mfma_f32_16x16x32_f16 v[142:145], v[66:69], v[98:101], v[142:145]
	v_mfma_f32_16x16x32_f16 v[134:137], v[74:77], v[98:101], v[134:137]
	v_mfma_f32_16x16x32_f16 v[126:129], v[66:69], v[176:179], v[126:129]
	v_mfma_f32_16x16x32_f16 v[118:121], v[74:77], v[176:179], v[118:121]
	v_mfma_f32_16x16x32_f16 v[110:113], v[66:69], v[184:187], v[110:113]
	v_mfma_f32_16x16x32_f16 v[106:109], v[74:77], v[184:187], v[106:109]
	v_mfma_f32_16x16x32_f16 v[142:145], v[70:73], v[102:105], v[142:145]
	v_mfma_f32_16x16x32_f16 v[134:137], v[78:81], v[102:105], v[134:137]
	v_mfma_f32_16x16x32_f16 v[126:129], v[70:73], v[180:183], v[126:129]
	v_mfma_f32_16x16x32_f16 v[118:121], v[78:81], v[180:183], v[118:121]
	v_mfma_f32_16x16x32_f16 v[110:113], v[70:73], v[188:191], v[110:113]
	v_mfma_f32_16x16x32_f16 v[106:109], v[78:81], v[188:191], v[106:109]
	v_mfma_f32_16x16x32_f16 v[146:149], v[204:207], v[90:93], v[146:149]
	v_mfma_f32_16x16x32_f16 v[150:153], v[196:199], v[90:93], v[150:153]
	v_mfma_f32_16x16x32_f16 v[146:149], v[220:223], v[94:97], v[146:149]
	v_mfma_f32_16x16x32_f16 v[138:141], v[196:199], v[98:101], v[138:141]
	v_mfma_f32_16x16x32_f16 v[150:153], v[200:203], v[94:97], v[150:153]
	v_mfma_f32_16x16x32_f16 v[138:141], v[200:203], v[102:105], v[138:141]
	v_mfma_f32_16x16x32_f16 v[130:133], v[204:207], v[98:101], v[130:133]
	v_mfma_f32_16x16x32_f16 v[130:133], v[220:223], v[102:105], v[130:133]
	v_mfma_f32_16x16x32_f16 v[122:125], v[196:199], v[176:179], v[122:125]
	v_mfma_f32_16x16x32_f16 v[122:125], v[200:203], v[180:183], v[122:125]
	v_mfma_f32_16x16x32_f16 v[114:117], v[204:207], v[176:179], v[114:117]
	v_mfma_f32_16x16x32_f16 v[86:89], v[196:199], v[184:187], v[86:89]
	v_mfma_f32_16x16x32_f16 v[82:85], v[204:207], v[184:187], v[82:85]
	v_mfma_f32_16x16x32_f16 v[114:117], v[220:223], v[180:183], v[114:117]
	v_mfma_f32_16x16x32_f16 v[86:89], v[200:203], v[188:191], v[86:89]
	v_mfma_f32_16x16x32_f16 v[82:85], v[220:223], v[188:191], v[82:85]
	s_barrier
	v_lshl_add_u64 v[224:225], v[192:193], 0, s[92:93]
	s_mov_b32 m0, s0
	s_nop 0
	global_load_lds_dwordx4 v[224:225], off
	v_lshl_add_u64 v[224:225], v[212:213], 0, s[92:93]
	s_add_i32 m0, s0, 0x2000
	s_nop 0
	global_load_lds_dwordx4 v[224:225], off
	s_mov_b32 m0, s89
	v_lshl_add_u64 v[192:193], v[214:215], 0, s[92:93]
	ds_read_b128 v[90:93], v195 offset:49152
	ds_read_b128 v[94:97], v195 offset:50176
	ds_read_b128 v[98:101], v195 offset:51200
	ds_read_b128 v[102:105], v195 offset:52224
	ds_read_b128 v[176:179], v195 offset:53248
	ds_read_b128 v[180:183], v195 offset:54272
	ds_read_b128 v[184:187], v195 offset:55296
	ds_read_b128 v[188:191], v195 offset:56320
	global_load_lds_dwordx4 v[192:193], off
	v_lshl_add_u64 v[192:193], v[216:217], 0, s[92:93]
	s_mov_b32 m0, s35
	s_nop 0
	global_load_lds_dwordx4 v[192:193], off
	s_add_u32 s0, s48, 0x80080
	s_addc_u32 s1, s49, 0
	s_add_i32 s26, s26, s64
	v_lshl_add_u64 v[224:225], s[0:1], 0, v[0:1]
	s_mov_b32 m0, s26
	s_nop 0
	global_load_lds_dwordx4 v[224:225], off
	v_lshl_add_u64 v[224:225], s[0:1], 0, v[162:163]
	s_add_i32 m0, s26, 0x2000
	s_nop 0
	global_load_lds_dwordx4 v[224:225], off
	s_add_i32 s60, s60, 2
	s_add_u32 vcc_lo, vcc_lo, 0x100
	s_addc_u32 vcc_hi, vcc_hi, 0
	s_add_u32 s21, s21, 0x100
	s_addc_u32 s66, s66, 0
	s_cmp_gt_u32 s60, 29
	s_waitcnt vmcnt(8) lgkmcnt(0)
	s_barrier
	v_mfma_f32_16x16x32_f16 v[62:65], v[66:69], v[90:93], v[62:65]
	v_mfma_f32_16x16x32_f16 v[58:61], v[74:77], v[90:93], v[58:61]
	v_mfma_f32_16x16x32_f16 v[46:49], v[66:69], v[98:101], v[46:49]
	v_mfma_f32_16x16x32_f16 v[38:41], v[74:77], v[98:101], v[38:41]
	v_mfma_f32_16x16x32_f16 v[30:33], v[66:69], v[176:179], v[30:33]
	v_mfma_f32_16x16x32_f16 v[22:25], v[74:77], v[176:179], v[22:25]
	v_mfma_f32_16x16x32_f16 v[14:17], v[66:69], v[184:187], v[14:17]
	v_mfma_f32_16x16x32_f16 v[10:13], v[74:77], v[184:187], v[10:13]
	v_mfma_f32_16x16x32_f16 v[62:65], v[70:73], v[94:97], v[62:65]
	v_mfma_f32_16x16x32_f16 v[58:61], v[78:81], v[94:97], v[58:61]
	v_mfma_f32_16x16x32_f16 v[46:49], v[70:73], v[102:105], v[46:49]
	v_mfma_f32_16x16x32_f16 v[38:41], v[78:81], v[102:105], v[38:41]
	v_mfma_f32_16x16x32_f16 v[30:33], v[70:73], v[180:183], v[30:33]
	v_mfma_f32_16x16x32_f16 v[22:25], v[78:81], v[180:183], v[22:25]
	v_mfma_f32_16x16x32_f16 v[14:17], v[70:73], v[188:191], v[14:17]
	v_mfma_f32_16x16x32_f16 v[10:13], v[78:81], v[188:191], v[10:13]
	v_mfma_f32_16x16x32_f16 v[54:57], v[196:199], v[90:93], v[54:57]
	v_mfma_f32_16x16x32_f16 v[50:53], v[204:207], v[90:93], v[50:53]
	v_mfma_f32_16x16x32_f16 v[42:45], v[196:199], v[98:101], v[42:45]
	v_mfma_f32_16x16x32_f16 v[34:37], v[204:207], v[98:101], v[34:37]
	v_mfma_f32_16x16x32_f16 v[26:29], v[196:199], v[176:179], v[26:29]
	v_mfma_f32_16x16x32_f16 v[18:21], v[204:207], v[176:179], v[18:21]
	v_mfma_f32_16x16x32_f16 v[6:9], v[196:199], v[184:187], v[6:9]
	v_mfma_f32_16x16x32_f16 v[2:5], v[204:207], v[184:187], v[2:5]
	v_mfma_f32_16x16x32_f16 v[54:57], v[200:203], v[94:97], v[54:57]
	v_mfma_f32_16x16x32_f16 v[50:53], v[220:223], v[94:97], v[50:53]
	v_mfma_f32_16x16x32_f16 v[42:45], v[200:203], v[102:105], v[42:45]
	v_mfma_f32_16x16x32_f16 v[34:37], v[220:223], v[102:105], v[34:37]
	v_mfma_f32_16x16x32_f16 v[26:29], v[200:203], v[180:183], v[26:29]
	v_mfma_f32_16x16x32_f16 v[18:21], v[220:223], v[180:183], v[18:21]
	v_mfma_f32_16x16x32_f16 v[6:9], v[200:203], v[188:191], v[6:9]
	v_mfma_f32_16x16x32_f16 v[2:5], v[220:223], v[188:191], v[2:5]
	s_barrier
	s_cbranch_scc1 .Lg4x_92

; #define PG8_STAGE(bufoff, gbase, voff) do { _Pragma("unroll") for (int _i = 0; _i < 2; ++_i) \
;         __builtin_amdgcn_global_load_lds((const unsigned*)((const char*)(gbase) + (voff)[_i]), (LAS unsigned*)(lds + (bufoff) + ldsw + _i * 8192), 16, 0, 0); } while (0)
; #define PG8_LDA(dst, b, h) do { _Pragma("unroll") for (int m = 0; m < 4; ++m) _Pragma("unroll") for (int k = 0; k < 2; ++k) dst[m][k] = *(const LAS h16x8*)(lds + PG8_SA(b, h) + aoff + m * 2048 + k * 1024); } while (0)
; #define PG8_LDB(dst, b, h) do { _Pragma("unroll") for (int n = 0; n < 2; ++n) _Pragma("unroll") for (int k = 0; k < 2; ++k) dst[n][k] = *(const LAS h16x8*)(lds + PG8_SB(b, h) + boff + n * 2048 + k * 1024); } while (0)
; #define PG8_MMA(ai, bj, At, Bt_) do { __builtin_amdgcn_s_setprio(1); _Pragma("unroll") for (int m = 0; m < 4; ++m) _Pragma("unroll") for (int n = 0; n < 2; ++n) _Pragma("unroll") for (int k = 0; k < 2; ++k) \
;         acc[ai][bj][m][n] = __builtin_amdgcn_mfma_f32_16x16x32_f16(Bt_[n][k], At[m][k], acc[ai][bj][m][n], 0, 0, 0); __builtin_amdgcn_s_setprio(0); } while (0)
; #define PG8_WAIT_V(n) asm volatile("s_waitcnt vmcnt(" #n ")" ::: "memory")
; #define PG8_WAIT_L(n) asm volatile("s_waitcnt lgkmcnt(" #n ")" ::: "memory")
; #define PG8_BAR __builtin_amdgcn_s_barrier()
; #define PG8_SCHED __builtin_amdgcn_sched_barrier(0)
; template <class Epi, class AMap>
; __device__ __forceinline__ void gemm_phase(LAS unsigned char* lds, const AMap am, const int lda, const h16* Bt, const int ldb, const int M, const int N, const int K, const Epi& E) {
;     ...
;             PG8_LDB(B0, 0, 0); PG8_SCHED; PG8_LDA(At, 0, 0); PG8_STAGE(PG8_SA(1, 1), a1 + hstepA, voffA);
;             PG8_WAIT_L(8); PG8_BAR; PG8_WAIT_L(0); PG8_MMA(0, 0, At, B0); PG8_BAR; PG8_SCHED;
;             PG8_LDB(B1, 0, 1); PG8_STAGE(PG8_SB(0, 0), b2, voffB);
;             PG8_BAR; PG8_WAIT_L(0); PG8_MMA(0, 1, At, B1); PG8_BAR;
;             PG8_LDA(At, 0, 1); PG8_STAGE(PG8_SA(0, 0), a2, voffA);
;             PG8_BAR; PG8_WAIT_L(0); PG8_MMA(1, 0, At, B0); PG8_BAR; PG8_SCHED;
;             PG8_STAGE(PG8_SB(0, 1), b2 + hstepB, voffB);
;             PG8_WAIT_V(6); PG8_BAR; PG8_MMA(1, 1, At, B1); PG8_BAR;
.Lg4p_147:
	s_add_u32 s46, s26, 0xfff80080
	s_addc_u32 s47, s27, -1
	s_add_i32 s60, 0, 0x10000
	v_add_u32_e32 v144, s60, v147
	ds_read_b128 v[140:143], v144
	ds_read_b128 v[150:153], v144 offset:1024
	ds_read_b128 v[154:157], v144 offset:2048
	ds_read_b128 v[158:161], v144 offset:3072
	s_cmp_eq_u32 s51, 28
	s_cselect_b32 s49, s41, s47
	s_cselect_b32 s48, s29, s46
	s_cselect_b32 s47, s1, s50
	s_cselect_b32 s46, s20, s21
	v_lshl_add_u64 v[144:145], s[26:27], 0, v[136:137]
	s_add_i32 m0, s23, 0xc000
	ds_read_b128 v[162:165], v149
	ds_read_b128 v[166:169], v149 offset:1024
	ds_read_b128 v[170:173], v149 offset:2048
	ds_read_b128 v[174:177], v149 offset:3072
	ds_read_b128 v[178:181], v149 offset:4096
	ds_read_b128 v[182:185], v149 offset:5120
	ds_read_b128 v[186:189], v149 offset:6144
	ds_read_b128 v[190:193], v149 offset:7168
	global_load_lds_dwordx4 v[144:145], off
	v_lshl_add_u64 v[144:145], s[26:27], 0, v[138:139]
	s_add_i32 m0, s23, 0xe000
	s_nop 0
	global_load_lds_dwordx4 v[144:145], off
	s_waitcnt lgkmcnt(11)
	s_add_i32 s66, 0, 0x14000
	v_add_u32_e32 v144, s66, v147
	s_add_i32 s60, s60, s64
	ds_read_b128 v[194:197], v144
	ds_read_b128 v[198:201], v144 offset:1024
	ds_read_b128 v[202:205], v144 offset:2048
	ds_read_b128 v[220:223], v144 offset:3072
	s_waitcnt vmcnt(40) lgkmcnt(0)
	s_barrier
	v_mfma_f32_16x16x32_f16 v[126:129], v[140:143], v[162:165], 0
	v_mfma_f32_16x16x32_f16 v[122:125], v[154:157], v[162:165], 0
	v_mfma_f32_16x16x32_f16 v[110:113], v[140:143], v[170:173], 0
	v_mfma_f32_16x16x32_f16 v[106:109], v[154:157], v[170:173], 0
	v_mfma_f32_16x16x32_f16 v[94:97], v[140:143], v[178:181], 0
	v_mfma_f32_16x16x32_f16 v[90:93], v[154:157], v[178:181], 0
	v_mfma_f32_16x16x32_f16 v[78:81], v[140:143], v[186:189], 0
	v_mfma_f32_16x16x32_f16 v[74:77], v[154:157], v[186:189], 0
	v_mfma_f32_16x16x32_f16 v[126:129], v[150:153], v[166:169], v[126:129]
	v_mfma_f32_16x16x32_f16 v[122:125], v[158:161], v[166:169], v[122:125]
	v_mfma_f32_16x16x32_f16 v[110:113], v[150:153], v[174:177], v[110:113]
	v_mfma_f32_16x16x32_f16 v[106:109], v[158:161], v[174:177], v[106:109]
	v_mfma_f32_16x16x32_f16 v[94:97], v[150:153], v[182:185], v[94:97]
	v_mfma_f32_16x16x32_f16 v[90:93], v[158:161], v[182:185], v[90:93]
	v_mfma_f32_16x16x32_f16 v[78:81], v[150:153], v[190:193], v[78:81]
	v_mfma_f32_16x16x32_f16 v[74:77], v[158:161], v[190:193], v[74:77]
	v_mfma_f32_16x16x32_f16 v[118:121], v[194:197], v[162:165], 0
	v_mfma_f32_16x16x32_f16 v[114:117], v[202:205], v[162:165], 0
	v_mfma_f32_16x16x32_f16 v[102:105], v[194:197], v[170:173], 0
	v_mfma_f32_16x16x32_f16 v[98:101], v[202:205], v[170:173], 0
	v_mfma_f32_16x16x32_f16 v[86:89], v[194:197], v[178:181], 0
	v_mfma_f32_16x16x32_f16 v[82:85], v[202:205], v[178:181], 0
	v_mfma_f32_16x16x32_f16 v[70:73], v[194:197], v[186:189], 0
	v_mfma_f32_16x16x32_f16 v[66:69], v[202:205], v[186:189], 0
	v_mfma_f32_16x16x32_f16 v[118:121], v[198:201], v[166:169], v[118:121]
	v_mfma_f32_16x16x32_f16 v[114:117], v[220:223], v[166:169], v[114:117]
	v_mfma_f32_16x16x32_f16 v[102:105], v[198:201], v[174:177], v[102:105]
	v_mfma_f32_16x16x32_f16 v[98:101], v[220:223], v[174:177], v[98:101]
	v_mfma_f32_16x16x32_f16 v[86:89], v[198:201], v[182:185], v[86:89]
	v_mfma_f32_16x16x32_f16 v[82:85], v[220:223], v[182:185], v[82:85]
	v_mfma_f32_16x16x32_f16 v[70:73], v[198:201], v[190:193], v[70:73]
	v_mfma_f32_16x16x32_f16 v[66:69], v[220:223], v[190:193], v[66:69]
	s_barrier
	v_lshl_add_u64 v[144:145], s[46:47], 0, v[0:1]
	s_mov_b32 m0, s60
	v_lshl_add_u64 v[206:207], s[46:47], 0, v[134:135]
	global_load_lds_dwordx4 v[144:145], off
	s_add_i32 m0, s60, 0x2000
	s_nop 0
	global_load_lds_dwordx4 v[206:207], off
	s_mov_b32 m0, s23
	v_lshl_add_u64 v[212:213], s[48:49], 0, v[130:131]
	ds_read_b128 v[162:165], v149 offset:16384
	ds_read_b128 v[166:169], v149 offset:17408
	ds_read_b128 v[170:173], v149 offset:18432
	ds_read_b128 v[174:177], v149 offset:19456
	ds_read_b128 v[178:181], v149 offset:20480
	ds_read_b128 v[182:185], v149 offset:21504
	ds_read_b128 v[186:189], v149 offset:22528
	ds_read_b128 v[190:193], v149 offset:23552
	global_load_lds_dwordx4 v[212:213], off
	v_lshl_add_u64 v[214:215], s[48:49], 0, v[132:133]
	s_mov_b32 m0, s71
	s_nop 0
	global_load_lds_dwordx4 v[214:215], off
	s_add_u32 s78, s46, 0x80000
	s_addc_u32 s79, s47, 0
	s_add_i32 s60, s66, s64
	v_lshl_add_u64 v[232:233], s[78:79], 0, v[0:1]
	s_mov_b32 m0, s60
	s_nop 0
	global_load_lds_dwordx4 v[232:233], off
	v_lshl_add_u64 v[232:233], s[78:79], 0, v[134:135]
	s_add_i32 m0, s60, 0x2000
	s_nop 0
	global_load_lds_dwordx4 v[232:233], off
	s_waitcnt vmcnt(8) lgkmcnt(0)
	s_barrier
; #define PG8_STAGE(bufoff, gbase, voff) do { _Pragma("unroll") for (int _i = 0; _i < 2; ++_i) \
;         __builtin_amdgcn_global_load_lds((const unsigned*)((const char*)(gbase) + (voff)[_i]), (LAS unsigned*)(lds + (bufoff) + ldsw + _i * 8192), 16, 0, 0); } while (0)
; #define PG8_LDA(dst, b, h) do { _Pragma("unroll") for (int m = 0; m < 4; ++m) _Pragma("unroll") for (int k = 0; k < 2; ++k) dst[m][k] = *(const LAS h16x8*)(lds + PG8_SA(b, h) + aoff + m * 2048 + k * 1024); } while (0)
; #define PG8_LDB(dst, b, h) do { _Pragma("unroll") for (int n = 0; n < 2; ++n) _Pragma("unroll") for (int k = 0; k < 2; ++k) dst[n][k] = *(const LAS h16x8*)(lds + PG8_SB(b, h) + boff + n * 2048 + k * 1024); } while (0)
; #define PG8_MMA(ai, bj, At, Bt_) do { __builtin_amdgcn_s_setprio(1); _Pragma("unroll") for (int m = 0; m < 4; ++m) _Pragma("unroll") for (int n = 0; n < 2; ++n) _Pragma("unroll") for (int k = 0; k < 2; ++k) \
;         acc[ai][bj][m][n] = __builtin_amdgcn_mfma_f32_16x16x32_f16(Bt_[n][k], At[m][k], acc[ai][bj][m][n], 0, 0, 0); __builtin_amdgcn_s_setprio(0); } while (0)
; #define PG8_WAIT_V(n) asm volatile("s_waitcnt vmcnt(" #n ")" ::: "memory")
; #define PG8_WAIT_L(n) asm volatile("s_waitcnt lgkmcnt(" #n ")" ::: "memory")
; #define PG8_BAR __builtin_amdgcn_s_barrier()
; #define PG8_SCHED __builtin_amdgcn_sched_barrier(0)
; template <class Epi, class AMap>
; __device__ __forceinline__ void gemm_phase(LAS unsigned char* lds, const AMap am, const int lda, const h16* Bt, const int ldb, const int M, const int N, const int K, const Epi& E) {
;     ...
;             PG8_WAIT_V(6); PG8_BAR; PG8_MMA(1, 1, At, B1); PG8_BAR;
;             PG8_LDB(B0, 1, 0); PG8_SCHED; PG8_LDA(At, 1, 0); PG8_STAGE(PG8_SA(0, 1), a2 + hstepA, voffA);
;             PG8_WAIT_L(8); PG8_BAR; PG8_WAIT_L(0); PG8_MMA(0, 0, At, B0); PG8_BAR; PG8_SCHED;
;             PG8_LDB(B1, 1, 1); PG8_STAGE(PG8_SB(1, 0), b3, voffB);
;             PG8_BAR; PG8_WAIT_L(0); PG8_MMA(0, 1, At, B1); PG8_BAR;
	v_mfma_f32_16x16x32_f16 v[62:65], v[140:143], v[162:165], 0
	v_mfma_f32_16x16x32_f16 v[58:61], v[154:157], v[162:165], 0
	v_mfma_f32_16x16x32_f16 v[46:49], v[140:143], v[170:173], 0
	v_mfma_f32_16x16x32_f16 v[42:45], v[154:157], v[170:173], 0
	v_mfma_f32_16x16x32_f16 v[30:33], v[140:143], v[178:181], 0
	v_mfma_f32_16x16x32_f16 v[26:29], v[154:157], v[178:181], 0
	v_mfma_f32_16x16x32_f16 v[14:17], v[140:143], v[186:189], 0
	v_mfma_f32_16x16x32_f16 v[10:13], v[154:157], v[186:189], 0
	v_mfma_f32_16x16x32_f16 v[62:65], v[150:153], v[166:169], v[62:65]
	v_mfma_f32_16x16x32_f16 v[58:61], v[158:161], v[166:169], v[58:61]
	v_mfma_f32_16x16x32_f16 v[46:49], v[150:153], v[174:177], v[46:49]
	v_mfma_f32_16x16x32_f16 v[42:45], v[158:161], v[174:177], v[42:45]
	v_mfma_f32_16x16x32_f16 v[30:33], v[150:153], v[182:185], v[30:33]
	v_mfma_f32_16x16x32_f16 v[26:29], v[158:161], v[182:185], v[26:29]
	v_mfma_f32_16x16x32_f16 v[14:17], v[150:153], v[190:193], v[14:17]
	v_mfma_f32_16x16x32_f16 v[10:13], v[158:161], v[190:193], v[10:13]
	v_mfma_f32_16x16x32_f16 v[54:57], v[194:197], v[162:165], 0
	v_mfma_f32_16x16x32_f16 v[50:53], v[202:205], v[162:165], 0
	v_mfma_f32_16x16x32_f16 v[38:41], v[194:197], v[170:173], 0
	v_mfma_f32_16x16x32_f16 v[34:37], v[202:205], v[170:173], 0
	v_mfma_f32_16x16x32_f16 v[22:25], v[194:197], v[178:181], 0
	v_mfma_f32_16x16x32_f16 v[18:21], v[202:205], v[178:181], 0
	v_mfma_f32_16x16x32_f16 v[6:9], v[194:197], v[186:189], 0
	v_mfma_f32_16x16x32_f16 v[2:5], v[202:205], v[186:189], 0
	v_mfma_f32_16x16x32_f16 v[54:57], v[198:201], v[166:169], v[54:57]
	v_mfma_f32_16x16x32_f16 v[50:53], v[220:223], v[166:169], v[50:53]
	v_mfma_f32_16x16x32_f16 v[38:41], v[198:201], v[174:177], v[38:41]
	v_mfma_f32_16x16x32_f16 v[34:37], v[220:223], v[174:177], v[34:37]
	v_mfma_f32_16x16x32_f16 v[22:25], v[198:201], v[182:185], v[22:25]
	v_mfma_f32_16x16x32_f16 v[18:21], v[220:223], v[182:185], v[18:21]
	v_mfma_f32_16x16x32_f16 v[6:9], v[198:201], v[190:193], v[6:9]
	v_mfma_f32_16x16x32_f16 v[2:5], v[220:223], v[190:193], v[2:5]
	s_barrier
	s_add_i32 s60, 0, 0x18000
	v_add_u32_e32 v234, s60, v147
	ds_read_b128 v[140:143], v234
	ds_read_b128 v[150:153], v234 offset:1024
	ds_read_b128 v[154:157], v234 offset:2048
	ds_read_b128 v[158:161], v234 offset:3072
	s_add_u32 s48, s48, 0x80000
	s_addc_u32 s49, s49, 0
	s_mov_b32 m0, s72
	v_lshl_add_u64 v[232:233], s[48:49], 0, v[130:131]
	ds_read_b128 v[162:165], v149 offset:32768
	ds_read_b128 v[166:169], v149 offset:33792
	ds_read_b128 v[170:173], v149 offset:34816
	ds_read_b128 v[174:177], v149 offset:35840
	ds_read_b128 v[178:181], v149 offset:36864
	ds_read_b128 v[182:185], v149 offset:37888
	ds_read_b128 v[186:189], v149 offset:38912
	ds_read_b128 v[190:193], v149 offset:39936
	global_load_lds_dwordx4 v[232:233], off
	v_lshl_add_u64 v[232:233], s[48:49], 0, v[132:133]
	s_mov_b32 m0, s73
	s_nop 0
	global_load_lds_dwordx4 v[232:233], off
	s_waitcnt lgkmcnt(11)
	s_add_i32 s48, 0, 0x1c000
	s_add_i32 s49, s60, s64
	v_add_u32_e32 v216, s48, v147
	v_lshl_add_u64 v[144:145], v[144:145], 0, s[92:93]
	s_mov_b32 m0, s49
	ds_read_b128 v[194:197], v216
	ds_read_b128 v[198:201], v216 offset:1024
	ds_read_b128 v[202:205], v216 offset:2048
	ds_read_b128 v[220:223], v216 offset:3072
	s_waitcnt vmcnt(8) lgkmcnt(0)
	s_barrier
	v_mfma_f32_16x16x32_f16 v[126:129], v[140:143], v[162:165], v[126:129]
	v_mfma_f32_16x16x32_f16 v[122:125], v[154:157], v[162:165], v[122:125]
	v_mfma_f32_16x16x32_f16 v[110:113], v[140:143], v[170:173], v[110:113]
	v_mfma_f32_16x16x32_f16 v[106:109], v[154:157], v[170:173], v[106:109]
	v_mfma_f32_16x16x32_f16 v[94:97], v[140:143], v[178:181], v[94:97]
	v_mfma_f32_16x16x32_f16 v[90:93], v[154:157], v[178:181], v[90:93]
	v_mfma_f32_16x16x32_f16 v[78:81], v[140:143], v[186:189], v[78:81]
	v_mfma_f32_16x16x32_f16 v[74:77], v[154:157], v[186:189], v[74:77]
	v_mfma_f32_16x16x32_f16 v[126:129], v[150:153], v[166:169], v[126:129]
	v_mfma_f32_16x16x32_f16 v[122:125], v[158:161], v[166:169], v[122:125]
	v_mfma_f32_16x16x32_f16 v[110:113], v[150:153], v[174:177], v[110:113]
	v_mfma_f32_16x16x32_f16 v[106:109], v[158:161], v[174:177], v[106:109]
	v_mfma_f32_16x16x32_f16 v[94:97], v[150:153], v[182:185], v[94:97]
	v_mfma_f32_16x16x32_f16 v[90:93], v[158:161], v[182:185], v[90:93]
	v_mfma_f32_16x16x32_f16 v[78:81], v[150:153], v[190:193], v[78:81]
	v_mfma_f32_16x16x32_f16 v[74:77], v[158:161], v[190:193], v[74:77]
	v_mfma_f32_16x16x32_f16 v[118:121], v[194:197], v[162:165], v[118:121]
	v_mfma_f32_16x16x32_f16 v[114:117], v[202:205], v[162:165], v[114:117]
	v_mfma_f32_16x16x32_f16 v[102:105], v[194:197], v[170:173], v[102:105]
	v_mfma_f32_16x16x32_f16 v[98:101], v[202:205], v[170:173], v[98:101]
	v_mfma_f32_16x16x32_f16 v[86:89], v[194:197], v[178:181], v[86:89]
	v_mfma_f32_16x16x32_f16 v[82:85], v[202:205], v[178:181], v[82:85]
	v_mfma_f32_16x16x32_f16 v[70:73], v[194:197], v[186:189], v[70:73]
	v_mfma_f32_16x16x32_f16 v[66:69], v[202:205], v[186:189], v[66:69]
	v_mfma_f32_16x16x32_f16 v[118:121], v[198:201], v[166:169], v[118:121]
	v_mfma_f32_16x16x32_f16 v[114:117], v[220:223], v[166:169], v[114:117]
	v_mfma_f32_16x16x32_f16 v[102:105], v[198:201], v[174:177], v[102:105]
	v_mfma_f32_16x16x32_f16 v[98:101], v[220:223], v[174:177], v[98:101]
	v_mfma_f32_16x16x32_f16 v[86:89], v[198:201], v[182:185], v[86:89]
	v_mfma_f32_16x16x32_f16 v[82:85], v[220:223], v[182:185], v[82:85]
	v_mfma_f32_16x16x32_f16 v[70:73], v[198:201], v[190:193], v[70:73]
	v_mfma_f32_16x16x32_f16 v[66:69], v[220:223], v[190:193], v[66:69]
	s_barrier
; #define PG8_STAGE(bufoff, gbase, voff) do { _Pragma("unroll") for (int _i = 0; _i < 2; ++_i) \
;         __builtin_amdgcn_global_load_lds((const unsigned*)((const char*)(gbase) + (voff)[_i]), (LAS unsigned*)(lds + (bufoff) + ldsw + _i * 8192), 16, 0, 0); } while (0)
; #define PG8_LDA(dst, b, h) do { _Pragma("unroll") for (int m = 0; m < 4; ++m) _Pragma("unroll") for (int k = 0; k < 2; ++k) dst[m][k] = *(const LAS h16x8*)(lds + PG8_SA(b, h) + aoff + m * 2048 + k * 1024); } while (0)
; #define PG8_MMA(ai, bj, At, Bt_) do { __builtin_amdgcn_s_setprio(1); _Pragma("unroll") for (int m = 0; m < 4; ++m) _Pragma("unroll") for (int n = 0; n < 2; ++n) _Pragma("unroll") for (int k = 0; k < 2; ++k) \
;         acc[ai][bj][m][n] = __builtin_amdgcn_mfma_f32_16x16x32_f16(Bt_[n][k], At[m][k], acc[ai][bj][m][n], 0, 0, 0); __builtin_amdgcn_s_setprio(0); } while (0)
; #define PG8_WAIT_V(n) asm volatile("s_waitcnt vmcnt(" #n ")" ::: "memory")
; #define PG8_WAIT_L(n) asm volatile("s_waitcnt lgkmcnt(" #n ")" ::: "memory")
; #define PG8_BAR __builtin_amdgcn_s_barrier()
; #define PG8_SCHED __builtin_amdgcn_sched_barrier(0)
; template <class Epi, class AMap>
; __device__ __forceinline__ void gemm_phase(LAS unsigned char* lds, const AMap am, const int lda, const h16* Bt, const int ldb, const int M, const int N, const int K, const Epi& E) {
;     ...
;             PG8_LDA(At, 1, 1); PG8_STAGE(PG8_SA(1, 0), a3, voffA);
;             PG8_BAR; PG8_WAIT_L(0); PG8_MMA(1, 0, At, B0); PG8_BAR; PG8_SCHED;
;             PG8_STAGE(PG8_SB(1, 1), b3 + hstepB, voffB);
;             PG8_WAIT_V(6); PG8_BAR; PG8_MMA(1, 1, At, B1); PG8_BAR;
	global_load_lds_dwordx4 v[144:145], off
	v_lshl_add_u64 v[144:145], v[206:207], 0, s[92:93]
	s_add_i32 m0, s49, 0x2000
	s_nop 0
	global_load_lds_dwordx4 v[144:145], off
	s_mov_b32 m0, s74
	v_lshl_add_u64 v[144:145], v[212:213], 0, s[92:93]
	ds_read_b128 v[162:165], v149 offset:49152
	ds_read_b128 v[166:169], v149 offset:50176
	ds_read_b128 v[170:173], v149 offset:51200
	ds_read_b128 v[174:177], v149 offset:52224
	ds_read_b128 v[178:181], v149 offset:53248
	ds_read_b128 v[182:185], v149 offset:54272
	ds_read_b128 v[186:189], v149 offset:55296
	ds_read_b128 v[190:193], v149 offset:56320
	global_load_lds_dwordx4 v[144:145], off
	v_lshl_add_u64 v[144:145], v[214:215], 0, s[92:93]
	s_mov_b32 m0, s75
	s_nop 0
	global_load_lds_dwordx4 v[144:145], off
	s_add_u32 s46, s46, 0x80080
	s_addc_u32 s47, s47, 0
	s_add_i32 s48, s48, s64
	v_lshl_add_u64 v[232:233], s[46:47], 0, v[0:1]
	s_mov_b32 m0, s48
	s_nop 0
	global_load_lds_dwordx4 v[232:233], off
	v_lshl_add_u64 v[232:233], s[46:47], 0, v[134:135]
	s_add_i32 m0, s48, 0x2000
	s_nop 0
	global_load_lds_dwordx4 v[232:233], off
	s_add_i32 s51, s51, 2
	s_add_u32 s26, s26, 0x100
	s_addc_u32 s27, s27, 0
	s_add_u32 s21, s21, 0x100
	s_addc_u32 s50, s50, 0
	s_cmp_gt_u32 s51, 29
	s_waitcnt vmcnt(8) lgkmcnt(0)
	s_barrier
	v_mfma_f32_16x16x32_f16 v[62:65], v[140:143], v[162:165], v[62:65]
	v_mfma_f32_16x16x32_f16 v[58:61], v[154:157], v[162:165], v[58:61]
	v_mfma_f32_16x16x32_f16 v[46:49], v[140:143], v[170:173], v[46:49]
	v_mfma_f32_16x16x32_f16 v[42:45], v[154:157], v[170:173], v[42:45]
	v_mfma_f32_16x16x32_f16 v[30:33], v[140:143], v[178:181], v[30:33]
	v_mfma_f32_16x16x32_f16 v[26:29], v[154:157], v[178:181], v[26:29]
	v_mfma_f32_16x16x32_f16 v[14:17], v[140:143], v[186:189], v[14:17]
	v_mfma_f32_16x16x32_f16 v[10:13], v[154:157], v[186:189], v[10:13]
	v_mfma_f32_16x16x32_f16 v[62:65], v[150:153], v[166:169], v[62:65]
	v_mfma_f32_16x16x32_f16 v[58:61], v[158:161], v[166:169], v[58:61]
	v_mfma_f32_16x16x32_f16 v[46:49], v[150:153], v[174:177], v[46:49]
	v_mfma_f32_16x16x32_f16 v[42:45], v[158:161], v[174:177], v[42:45]
	v_mfma_f32_16x16x32_f16 v[30:33], v[150:153], v[182:185], v[30:33]
	v_mfma_f32_16x16x32_f16 v[26:29], v[158:161], v[182:185], v[26:29]
	v_mfma_f32_16x16x32_f16 v[14:17], v[150:153], v[190:193], v[14:17]
	v_mfma_f32_16x16x32_f16 v[10:13], v[158:161], v[190:193], v[10:13]
	v_mfma_f32_16x16x32_f16 v[54:57], v[194:197], v[162:165], v[54:57]
	v_mfma_f32_16x16x32_f16 v[50:53], v[202:205], v[162:165], v[50:53]
	v_mfma_f32_16x16x32_f16 v[38:41], v[194:197], v[170:173], v[38:41]
	v_mfma_f32_16x16x32_f16 v[34:37], v[202:205], v[170:173], v[34:37]
	v_mfma_f32_16x16x32_f16 v[22:25], v[194:197], v[178:181], v[22:25]
	v_mfma_f32_16x16x32_f16 v[18:21], v[202:205], v[178:181], v[18:21]
	v_mfma_f32_16x16x32_f16 v[6:9], v[194:197], v[186:189], v[6:9]
	v_mfma_f32_16x16x32_f16 v[2:5], v[202:205], v[186:189], v[2:5]
	v_mfma_f32_16x16x32_f16 v[54:57], v[198:201], v[166:169], v[54:57]
	v_mfma_f32_16x16x32_f16 v[50:53], v[220:223], v[166:169], v[50:53]
	v_mfma_f32_16x16x32_f16 v[38:41], v[198:201], v[174:177], v[38:41]
	v_mfma_f32_16x16x32_f16 v[34:37], v[220:223], v[174:177], v[34:37]
	v_mfma_f32_16x16x32_f16 v[22:25], v[198:201], v[182:185], v[22:25]
	v_mfma_f32_16x16x32_f16 v[18:21], v[220:223], v[182:185], v[18:21]
	v_mfma_f32_16x16x32_f16 v[6:9], v[198:201], v[190:193], v[6:9]
	v_mfma_f32_16x16x32_f16 v[2:5], v[220:223], v[190:193], v[2:5]
	s_barrier
	s_cbranch_scc1 .Lg4x_147

; #define PG8_STAGE(bufoff, gbase, voff) do { _Pragma("unroll") for (int _i = 0; _i < 2; ++_i) \
;         __builtin_amdgcn_global_load_lds((const unsigned*)((const char*)(gbase) + (voff)[_i]), (LAS unsigned*)(lds + (bufoff) + ldsw + _i * 8192), 16, 0, 0); } while (0)
; #define PG8_LDA(dst, b, h) do { _Pragma("unroll") for (int m = 0; m < 4; ++m) _Pragma("unroll") for (int k = 0; k < 2; ++k) dst[m][k] = *(const LAS h16x8*)(lds + PG8_SA(b, h) + aoff + m * 2048 + k * 1024); } while (0)
; #define PG8_LDB(dst, b, h) do { _Pragma("unroll") for (int n = 0; n < 2; ++n) _Pragma("unroll") for (int k = 0; k < 2; ++k) dst[n][k] = *(const LAS h16x8*)(lds + PG8_SB(b, h) + boff + n * 2048 + k * 1024); } while (0)
; #define PG8_WAIT_V(n) asm volatile("s_waitcnt vmcnt(" #n ")" ::: "memory")
; #define PG8_WAIT_L(n) asm volatile("s_waitcnt lgkmcnt(" #n ")" ::: "memory")
; #define PG8_BAR __builtin_amdgcn_s_barrier()
; #define PG8_SCHED __builtin_amdgcn_sched_barrier(0)
; template <class Epi, class AMap>
; __device__ __forceinline__ void gemm_phase(LAS unsigned char* lds, const AMap am, const int lda, const h16* Bt, const int ldb, const int M, const int N, const int K, const Epi& E) {
;     ...
;         const bool has_next = S.next(ui + 1, nxt);
;         const char* nA = has_next ? am(nxt.pn) + (size_t)nxt.pm * tstepA : cA; const char* nB = has_next ? (const char*)Bt + (size_t)nxt.pn * tstepB : cB;
; #pragma unroll 1
;         for (int t = 0; t < nt; t += 2) {
;             const bool last = (t == nt - 2);
;             const char* a1 = cA + (size_t)(t + 1) * kstep;
;             const char* a2 = last ? nA : cA + (size_t)(t + 2) * kstep; const char* b2 = last ? nB : cB + (size_t)(t + 2) * kstep;
;             const char* a3 = a2 + kstep; const char* b3 = b2 + kstep;
;             PG8_LDB(B0, 0, 0); PG8_SCHED; PG8_LDA(At, 0, 0); PG8_STAGE(PG8_SA(1, 1), a1 + hstepA, voffA);
;             PG8_WAIT_L(8); PG8_BAR; PG8_WAIT_L(0); PG8_MMA(0, 0, At, B0); PG8_BAR; PG8_SCHED;
;             PG8_LDB(B1, 0, 1); PG8_STAGE(PG8_SB(0, 0), b2, voffB);
;             PG8_BAR; PG8_WAIT_L(0); PG8_MMA(0, 1, At, B1); PG8_BAR;
;             PG8_LDA(At, 0, 1); PG8_STAGE(PG8_SA(0, 0), a2, voffA);
;             PG8_BAR; PG8_WAIT_L(0); PG8_MMA(1, 0, At, B0); PG8_BAR; PG8_SCHED;
;             PG8_STAGE(PG8_SB(0, 1), b2 + hstepB, voffB);
;             PG8_WAIT_V(6); PG8_BAR; PG8_MMA(1, 1, At, B1); PG8_BAR;
.LBB0_267:
	s_ashr_i32 s45, s44, 31
	s_lshl_b64 s[20:21], s[44:45], 20
	s_add_u32 s68, s94, s20
	v_cmp_lt_i64_e32 vcc, s[48:49], v[218:219]
	s_addc_u32 s69, s95, s21
	s_and_b64 s[20:21], vcc, exec
	s_cselect_b32 s23, s69, s41
	s_cselect_b32 s27, s68, s40
	s_ashr_i32 s1, s0, 31
	s_lshl_b64 s[20:21], s[0:1], 20
	s_add_u32 s70, s9, s20
	s_addc_u32 s71, s11, s21
	s_and_b64 s[20:21], vcc, exec
	s_cselect_b32 s1, s71, s43
	s_cselect_b32 s20, s70, s42
	s_add_u32 s40, s40, 0x80080
	s_addc_u32 s41, s41, 0
	s_add_u32 s21, s42, 0x100
	s_addc_u32 s29, s43, 0
	s_mov_b32 s35, -2
.Lg4p_268:
	s_add_u32 s42, s40, 0xfff80080
	s_addc_u32 s43, s41, -1
	s_add_i32 s45, 0, 0x10000
	v_add_u32_e32 v0, s45, v149
	ds_read_b128 v[142:145], v0
	ds_read_b128 v[154:157], v0 offset:1024
	ds_read_b128 v[158:161], v0 offset:2048
	ds_read_b128 v[162:165], v0 offset:3072
	s_cmp_eq_u32 s35, 28
	s_cselect_b32 s49, s23, s43
	s_cselect_b32 s48, s27, s42
	s_cselect_b32 s43, s1, s29
	s_cselect_b32 s42, s20, s21
	v_lshl_add_u64 v[146:147], s[40:41], 0, v[138:139]
	s_add_i32 m0, s72, 0xc000
	ds_read_b128 v[166:169], v153
	ds_read_b128 v[170:173], v153 offset:1024
	ds_read_b128 v[174:177], v153 offset:2048
	ds_read_b128 v[178:181], v153 offset:3072
	ds_read_b128 v[182:185], v153 offset:4096
	ds_read_b128 v[186:189], v153 offset:5120
	ds_read_b128 v[190:193], v153 offset:6144
	ds_read_b128 v[194:197], v153 offset:7168
	global_load_lds_dwordx4 v[146:147], off
	v_lshl_add_u64 v[146:147], s[40:41], 0, v[140:141]
	s_add_i32 m0, s72, 0xe000
	s_nop 0
	global_load_lds_dwordx4 v[146:147], off
	s_waitcnt lgkmcnt(11)
	s_add_i32 s60, 0, 0x14000
	s_add_i32 s45, s45, s65
	v_add_u32_e32 v0, s60, v149
	v_lshl_add_u64 v[146:147], s[42:43], 0, v[132:133]
	s_mov_b32 m0, s45
	ds_read_b128 v[198:201], v0
	ds_read_b128 v[202:205], v0 offset:1024
	ds_read_b128 v[220:223], v0 offset:2048
	ds_read_b128 v[224:227], v0 offset:3072
	s_waitcnt vmcnt(8) lgkmcnt(0)
	s_barrier
	v_mfma_f32_16x16x32_f16 v[126:129], v[142:145], v[166:169], 0
	v_mfma_f32_16x16x32_f16 v[122:125], v[158:161], v[166:169], 0
	v_mfma_f32_16x16x32_f16 v[110:113], v[142:145], v[174:177], 0
	v_mfma_f32_16x16x32_f16 v[106:109], v[158:161], v[174:177], 0
	v_mfma_f32_16x16x32_f16 v[94:97], v[142:145], v[182:185], 0
	v_mfma_f32_16x16x32_f16 v[90:93], v[158:161], v[182:185], 0
	v_mfma_f32_16x16x32_f16 v[78:81], v[142:145], v[190:193], 0
	v_mfma_f32_16x16x32_f16 v[74:77], v[158:161], v[190:193], 0
	v_mfma_f32_16x16x32_f16 v[126:129], v[154:157], v[170:173], v[126:129]
	v_mfma_f32_16x16x32_f16 v[122:125], v[162:165], v[170:173], v[122:125]
	v_mfma_f32_16x16x32_f16 v[110:113], v[154:157], v[178:181], v[110:113]
	v_mfma_f32_16x16x32_f16 v[106:109], v[162:165], v[178:181], v[106:109]
	v_mfma_f32_16x16x32_f16 v[94:97], v[154:157], v[186:189], v[94:97]
	v_mfma_f32_16x16x32_f16 v[90:93], v[162:165], v[186:189], v[90:93]
	v_mfma_f32_16x16x32_f16 v[78:81], v[154:157], v[194:197], v[78:81]
	v_mfma_f32_16x16x32_f16 v[74:77], v[162:165], v[194:197], v[74:77]
	v_mfma_f32_16x16x32_f16 v[118:121], v[198:201], v[166:169], 0
	v_mfma_f32_16x16x32_f16 v[114:117], v[220:223], v[166:169], 0
	v_mfma_f32_16x16x32_f16 v[102:105], v[198:201], v[174:177], 0
	v_mfma_f32_16x16x32_f16 v[98:101], v[220:223], v[174:177], 0
	v_mfma_f32_16x16x32_f16 v[86:89], v[198:201], v[182:185], 0
	v_mfma_f32_16x16x32_f16 v[82:85], v[220:223], v[182:185], 0
	v_mfma_f32_16x16x32_f16 v[70:73], v[198:201], v[190:193], 0
	v_mfma_f32_16x16x32_f16 v[66:69], v[220:223], v[190:193], 0
	v_mfma_f32_16x16x32_f16 v[118:121], v[202:205], v[170:173], v[118:121]
	v_mfma_f32_16x16x32_f16 v[114:117], v[224:227], v[170:173], v[114:117]
	v_mfma_f32_16x16x32_f16 v[102:105], v[202:205], v[178:181], v[102:105]
	v_mfma_f32_16x16x32_f16 v[98:101], v[224:227], v[178:181], v[98:101]
	v_mfma_f32_16x16x32_f16 v[86:89], v[202:205], v[186:189], v[86:89]
	v_mfma_f32_16x16x32_f16 v[82:85], v[224:227], v[186:189], v[82:85]
	v_mfma_f32_16x16x32_f16 v[70:73], v[202:205], v[194:197], v[70:73]
	v_mfma_f32_16x16x32_f16 v[66:69], v[224:227], v[194:197], v[66:69]
	s_barrier
	global_load_lds_dwordx4 v[146:147], off
	v_lshl_add_u64 v[206:207], s[42:43], 0, v[136:137]
	s_add_i32 m0, s45, 0x2000
	s_nop 0
	global_load_lds_dwordx4 v[206:207], off
	s_mov_b32 m0, s72
	v_lshl_add_u64 v[212:213], s[48:49], 0, v[130:131]
	ds_read_b128 v[166:169], v153 offset:16384
	ds_read_b128 v[170:173], v153 offset:17408
	ds_read_b128 v[174:177], v153 offset:18432
	ds_read_b128 v[178:181], v153 offset:19456
	ds_read_b128 v[182:185], v153 offset:20480
	ds_read_b128 v[186:189], v153 offset:21504
	ds_read_b128 v[190:193], v153 offset:22528
	ds_read_b128 v[194:197], v153 offset:23552
	global_load_lds_dwordx4 v[212:213], off
	v_lshl_add_u64 v[228:229], s[48:49], 0, v[134:135]
	s_mov_b32 m0, s73
	s_nop 0
	global_load_lds_dwordx4 v[228:229], off
	s_add_u32 s50, s42, 0x80000
	s_addc_u32 s51, s43, 0
	s_add_i32 s45, s60, s65
	v_lshl_add_u64 v[232:233], s[50:51], 0, v[132:133]
	s_mov_b32 m0, s45
	s_nop 0
	global_load_lds_dwordx4 v[232:233], off
	v_lshl_add_u64 v[232:233], s[50:51], 0, v[136:137]
	s_add_i32 m0, s45, 0x2000
	s_nop 0
	global_load_lds_dwordx4 v[232:233], off
	s_waitcnt vmcnt(8) lgkmcnt(0)
	s_barrier
; #define PG8_STAGE(bufoff, gbase, voff) do { _Pragma("unroll") for (int _i = 0; _i < 2; ++_i) \
;         __builtin_amdgcn_global_load_lds((const unsigned*)((const char*)(gbase) + (voff)[_i]), (LAS unsigned*)(lds + (bufoff) + ldsw + _i * 8192), 16, 0, 0); } while (0)
; #define PG8_LDA(dst, b, h) do { _Pragma("unroll") for (int m = 0; m < 4; ++m) _Pragma("unroll") for (int k = 0; k < 2; ++k) dst[m][k] = *(const LAS h16x8*)(lds + PG8_SA(b, h) + aoff + m * 2048 + k * 1024); } while (0)
; #define PG8_LDB(dst, b, h) do { _Pragma("unroll") for (int n = 0; n < 2; ++n) _Pragma("unroll") for (int k = 0; k < 2; ++k) dst[n][k] = *(const LAS h16x8*)(lds + PG8_SB(b, h) + boff + n * 2048 + k * 1024); } while (0)
; #define PG8_MMA(ai, bj, At, Bt_) do { __builtin_amdgcn_s_setprio(1); _Pragma("unroll") for (int m = 0; m < 4; ++m) _Pragma("unroll") for (int n = 0; n < 2; ++n) _Pragma("unroll") for (int k = 0; k < 2; ++k) \
;         acc[ai][bj][m][n] = __builtin_amdgcn_mfma_f32_16x16x32_f16(Bt_[n][k], At[m][k], acc[ai][bj][m][n], 0, 0, 0); __builtin_amdgcn_s_setprio(0); } while (0)
; #define PG8_WAIT_V(n) asm volatile("s_waitcnt vmcnt(" #n ")" ::: "memory")
; #define PG8_WAIT_L(n) asm volatile("s_waitcnt lgkmcnt(" #n ")" ::: "memory")
; #define PG8_BAR __builtin_amdgcn_s_barrier()
; #define PG8_SCHED __builtin_amdgcn_sched_barrier(0)
; template <class Epi, class AMap>
; __device__ __forceinline__ void gemm_phase(LAS unsigned char* lds, const AMap am, const int lda, const h16* Bt, const int ldb, const int M, const int N, const int K, const Epi& E) {
;     ...
;             PG8_WAIT_V(6); PG8_BAR; PG8_MMA(1, 1, At, B1); PG8_BAR;
;             PG8_LDB(B0, 1, 0); PG8_SCHED; PG8_LDA(At, 1, 0); PG8_STAGE(PG8_SA(0, 1), a2 + hstepA, voffA);
;             PG8_WAIT_L(8); PG8_BAR; PG8_WAIT_L(0); PG8_MMA(0, 0, At, B0); PG8_BAR; PG8_SCHED;
;             PG8_LDB(B1, 1, 1); PG8_STAGE(PG8_SB(1, 0), b3, voffB);
;             PG8_BAR; PG8_WAIT_L(0); PG8_MMA(0, 1, At, B1); PG8_BAR;
	v_mfma_f32_16x16x32_f16 v[62:65], v[142:145], v[166:169], 0
	v_mfma_f32_16x16x32_f16 v[58:61], v[158:161], v[166:169], 0
	v_mfma_f32_16x16x32_f16 v[46:49], v[142:145], v[174:177], 0
	v_mfma_f32_16x16x32_f16 v[42:45], v[158:161], v[174:177], 0
	v_mfma_f32_16x16x32_f16 v[30:33], v[142:145], v[182:185], 0
	v_mfma_f32_16x16x32_f16 v[26:29], v[158:161], v[182:185], 0
	v_mfma_f32_16x16x32_f16 v[14:17], v[142:145], v[190:193], 0
	v_mfma_f32_16x16x32_f16 v[10:13], v[158:161], v[190:193], 0
	v_mfma_f32_16x16x32_f16 v[62:65], v[154:157], v[170:173], v[62:65]
	v_mfma_f32_16x16x32_f16 v[58:61], v[162:165], v[170:173], v[58:61]
	v_mfma_f32_16x16x32_f16 v[46:49], v[154:157], v[178:181], v[46:49]
	v_mfma_f32_16x16x32_f16 v[42:45], v[162:165], v[178:181], v[42:45]
	v_mfma_f32_16x16x32_f16 v[30:33], v[154:157], v[186:189], v[30:33]
	v_mfma_f32_16x16x32_f16 v[26:29], v[162:165], v[186:189], v[26:29]
	v_mfma_f32_16x16x32_f16 v[14:17], v[154:157], v[194:197], v[14:17]
	v_mfma_f32_16x16x32_f16 v[10:13], v[162:165], v[194:197], v[10:13]
	v_mfma_f32_16x16x32_f16 v[54:57], v[198:201], v[166:169], 0
	v_mfma_f32_16x16x32_f16 v[50:53], v[220:223], v[166:169], 0
	v_mfma_f32_16x16x32_f16 v[38:41], v[198:201], v[174:177], 0
	v_mfma_f32_16x16x32_f16 v[34:37], v[220:223], v[174:177], 0
	v_mfma_f32_16x16x32_f16 v[22:25], v[198:201], v[182:185], 0
	v_mfma_f32_16x16x32_f16 v[18:21], v[220:223], v[182:185], 0
	v_mfma_f32_16x16x32_f16 v[6:9], v[198:201], v[190:193], 0
	v_mfma_f32_16x16x32_f16 v[2:5], v[220:223], v[190:193], 0
	v_mfma_f32_16x16x32_f16 v[54:57], v[202:205], v[170:173], v[54:57]
	v_mfma_f32_16x16x32_f16 v[50:53], v[224:227], v[170:173], v[50:53]
	v_mfma_f32_16x16x32_f16 v[38:41], v[202:205], v[178:181], v[38:41]
	v_mfma_f32_16x16x32_f16 v[34:37], v[224:227], v[178:181], v[34:37]
	v_mfma_f32_16x16x32_f16 v[22:25], v[202:205], v[186:189], v[22:25]
	v_mfma_f32_16x16x32_f16 v[18:21], v[224:227], v[186:189], v[18:21]
	v_mfma_f32_16x16x32_f16 v[6:9], v[202:205], v[194:197], v[6:9]
	v_mfma_f32_16x16x32_f16 v[2:5], v[224:227], v[194:197], v[2:5]
	s_barrier
	s_add_i32 s45, 0, 0x18000
	v_add_u32_e32 v0, s45, v149
	ds_read_b128 v[142:145], v0
	ds_read_b128 v[154:157], v0 offset:1024
	ds_read_b128 v[158:161], v0 offset:2048
	ds_read_b128 v[162:165], v0 offset:3072
	s_add_u32 s48, s48, 0x80000
	s_addc_u32 s49, s49, 0
	s_mov_b32 m0, s74
	v_lshl_add_u64 v[232:233], s[48:49], 0, v[130:131]
	ds_read_b128 v[166:169], v153 offset:32768
	ds_read_b128 v[170:173], v153 offset:33792
	ds_read_b128 v[174:177], v153 offset:34816
	ds_read_b128 v[178:181], v153 offset:35840
	ds_read_b128 v[182:185], v153 offset:36864
	ds_read_b128 v[186:189], v153 offset:37888
	ds_read_b128 v[190:193], v153 offset:38912
	ds_read_b128 v[194:197], v153 offset:39936
	global_load_lds_dwordx4 v[232:233], off
	v_lshl_add_u64 v[232:233], s[48:49], 0, v[134:135]
	s_mov_b32 m0, s75
	s_nop 0
	global_load_lds_dwordx4 v[232:233], off
	s_waitcnt lgkmcnt(11)
	s_add_i32 s48, 0, 0x1c000
	s_add_i32 s45, s45, s65
	v_add_u32_e32 v0, s48, v149
	v_lshl_add_u64 v[146:147], v[146:147], 0, s[92:93]
	s_mov_b32 m0, s45
	ds_read_b128 v[198:201], v0
	ds_read_b128 v[202:205], v0 offset:1024
	ds_read_b128 v[220:223], v0 offset:2048
	ds_read_b128 v[224:227], v0 offset:3072
	s_waitcnt vmcnt(8) lgkmcnt(0)
	s_barrier
	v_mfma_f32_16x16x32_f16 v[126:129], v[142:145], v[166:169], v[126:129]
	v_mfma_f32_16x16x32_f16 v[122:125], v[158:161], v[166:169], v[122:125]
	v_mfma_f32_16x16x32_f16 v[110:113], v[142:145], v[174:177], v[110:113]
	v_mfma_f32_16x16x32_f16 v[106:109], v[158:161], v[174:177], v[106:109]
	v_mfma_f32_16x16x32_f16 v[94:97], v[142:145], v[182:185], v[94:97]
	v_mfma_f32_16x16x32_f16 v[90:93], v[158:161], v[182:185], v[90:93]
	v_mfma_f32_16x16x32_f16 v[78:81], v[142:145], v[190:193], v[78:81]
	v_mfma_f32_16x16x32_f16 v[74:77], v[158:161], v[190:193], v[74:77]
	v_mfma_f32_16x16x32_f16 v[126:129], v[154:157], v[170:173], v[126:129]
	v_mfma_f32_16x16x32_f16 v[122:125], v[162:165], v[170:173], v[122:125]
	v_mfma_f32_16x16x32_f16 v[110:113], v[154:157], v[178:181], v[110:113]
	v_mfma_f32_16x16x32_f16 v[106:109], v[162:165], v[178:181], v[106:109]
	v_mfma_f32_16x16x32_f16 v[94:97], v[154:157], v[186:189], v[94:97]
	v_mfma_f32_16x16x32_f16 v[90:93], v[162:165], v[186:189], v[90:93]
	v_mfma_f32_16x16x32_f16 v[78:81], v[154:157], v[194:197], v[78:81]
	v_mfma_f32_16x16x32_f16 v[74:77], v[162:165], v[194:197], v[74:77]
	v_mfma_f32_16x16x32_f16 v[118:121], v[198:201], v[166:169], v[118:121]
	v_mfma_f32_16x16x32_f16 v[114:117], v[220:223], v[166:169], v[114:117]
	v_mfma_f32_16x16x32_f16 v[102:105], v[198:201], v[174:177], v[102:105]
	v_mfma_f32_16x16x32_f16 v[98:101], v[220:223], v[174:177], v[98:101]
	v_mfma_f32_16x16x32_f16 v[86:89], v[198:201], v[182:185], v[86:89]
	v_mfma_f32_16x16x32_f16 v[82:85], v[220:223], v[182:185], v[82:85]
	v_mfma_f32_16x16x32_f16 v[70:73], v[198:201], v[190:193], v[70:73]
	v_mfma_f32_16x16x32_f16 v[66:69], v[220:223], v[190:193], v[66:69]
	v_mfma_f32_16x16x32_f16 v[118:121], v[202:205], v[170:173], v[118:121]
	v_mfma_f32_16x16x32_f16 v[114:117], v[224:227], v[170:173], v[114:117]
	v_mfma_f32_16x16x32_f16 v[102:105], v[202:205], v[178:181], v[102:105]
	v_mfma_f32_16x16x32_f16 v[98:101], v[224:227], v[178:181], v[98:101]
	v_mfma_f32_16x16x32_f16 v[86:89], v[202:205], v[186:189], v[86:89]
	v_mfma_f32_16x16x32_f16 v[82:85], v[224:227], v[186:189], v[82:85]
	v_mfma_f32_16x16x32_f16 v[70:73], v[202:205], v[194:197], v[70:73]
	v_mfma_f32_16x16x32_f16 v[66:69], v[224:227], v[194:197], v[66:69]
	s_barrier
; #define PG8_STAGE(bufoff, gbase, voff) do { _Pragma("unroll") for (int _i = 0; _i < 2; ++_i) \
;         __builtin_amdgcn_global_load_lds((const unsigned*)((const char*)(gbase) + (voff)[_i]), (LAS unsigned*)(lds + (bufoff) + ldsw + _i * 8192), 16, 0, 0); } while (0)
; #define PG8_LDA(dst, b, h) do { _Pragma("unroll") for (int m = 0; m < 4; ++m) _Pragma("unroll") for (int k = 0; k < 2; ++k) dst[m][k] = *(const LAS h16x8*)(lds + PG8_SA(b, h) + aoff + m * 2048 + k * 1024); } while (0)
; #define PG8_MMA(ai, bj, At, Bt_) do { __builtin_amdgcn_s_setprio(1); _Pragma("unroll") for (int m = 0; m < 4; ++m) _Pragma("unroll") for (int n = 0; n < 2; ++n) _Pragma("unroll") for (int k = 0; k < 2; ++k) \
;         acc[ai][bj][m][n] = __builtin_amdgcn_mfma_f32_16x16x32_f16(Bt_[n][k], At[m][k], acc[ai][bj][m][n], 0, 0, 0); __builtin_amdgcn_s_setprio(0); } while (0)
; #define PG8_WAIT_V(n) asm volatile("s_waitcnt vmcnt(" #n ")" ::: "memory")
; #define PG8_WAIT_L(n) asm volatile("s_waitcnt lgkmcnt(" #n ")" ::: "memory")
; #define PG8_BAR __builtin_amdgcn_s_barrier()
; #define PG8_SCHED __builtin_amdgcn_sched_barrier(0)
; template <class Epi, class AMap>
; __device__ __forceinline__ void gemm_phase(LAS unsigned char* lds, const AMap am, const int lda, const h16* Bt, const int ldb, const int M, const int N, const int K, const Epi& E) {
;     ...
;             PG8_LDA(At, 1, 1); PG8_STAGE(PG8_SA(1, 0), a3, voffA);
;             PG8_BAR; PG8_WAIT_L(0); PG8_MMA(1, 0, At, B0); PG8_BAR; PG8_SCHED;
;             PG8_STAGE(PG8_SB(1, 1), b3 + hstepB, voffB);
;             PG8_WAIT_V(6); PG8_BAR; PG8_MMA(1, 1, At, B1); PG8_BAR;
	global_load_lds_dwordx4 v[146:147], off
	v_lshl_add_u64 v[146:147], v[206:207], 0, s[92:93]
	s_add_i32 m0, s45, 0x2000
	s_nop 0
	global_load_lds_dwordx4 v[146:147], off
	s_mov_b32 m0, s77
	v_lshl_add_u64 v[146:147], v[212:213], 0, s[92:93]
	ds_read_b128 v[166:169], v153 offset:49152
	ds_read_b128 v[170:173], v153 offset:50176
	ds_read_b128 v[174:177], v153 offset:51200
	ds_read_b128 v[178:181], v153 offset:52224
	ds_read_b128 v[182:185], v153 offset:53248
	ds_read_b128 v[186:189], v153 offset:54272
	ds_read_b128 v[190:193], v153 offset:55296
	ds_read_b128 v[194:197], v153 offset:56320
	global_load_lds_dwordx4 v[146:147], off
	v_lshl_add_u64 v[146:147], v[228:229], 0, s[92:93]
	s_mov_b32 m0, s78
	s_nop 0
	global_load_lds_dwordx4 v[146:147], off
	s_add_u32 s42, s42, 0x80080
	s_addc_u32 s43, s43, 0
	s_add_i32 s45, s48, s65
	v_lshl_add_u64 v[232:233], s[42:43], 0, v[132:133]
	s_mov_b32 m0, s45
	s_nop 0
	global_load_lds_dwordx4 v[232:233], off
	v_lshl_add_u64 v[232:233], s[42:43], 0, v[136:137]
	s_add_i32 m0, s45, 0x2000
	s_nop 0
	global_load_lds_dwordx4 v[232:233], off
	s_add_i32 s35, s35, 2
	s_add_u32 s40, s40, 0x100
	s_addc_u32 s41, s41, 0
	s_add_u32 s21, s21, 0x100
	s_addc_u32 s29, s29, 0
	s_cmp_gt_u32 s35, 29
	s_waitcnt vmcnt(8) lgkmcnt(0)
	s_barrier
	v_mfma_f32_16x16x32_f16 v[62:65], v[142:145], v[166:169], v[62:65]
	v_mfma_f32_16x16x32_f16 v[58:61], v[158:161], v[166:169], v[58:61]
	v_mfma_f32_16x16x32_f16 v[46:49], v[142:145], v[174:177], v[46:49]
	v_mfma_f32_16x16x32_f16 v[42:45], v[158:161], v[174:177], v[42:45]
	v_mfma_f32_16x16x32_f16 v[30:33], v[142:145], v[182:185], v[30:33]
	v_mfma_f32_16x16x32_f16 v[26:29], v[158:161], v[182:185], v[26:29]
	v_mfma_f32_16x16x32_f16 v[14:17], v[142:145], v[190:193], v[14:17]
	v_mfma_f32_16x16x32_f16 v[10:13], v[158:161], v[190:193], v[10:13]
	v_mfma_f32_16x16x32_f16 v[62:65], v[154:157], v[170:173], v[62:65]
	v_mfma_f32_16x16x32_f16 v[58:61], v[162:165], v[170:173], v[58:61]
	v_mfma_f32_16x16x32_f16 v[46:49], v[154:157], v[178:181], v[46:49]
	v_mfma_f32_16x16x32_f16 v[42:45], v[162:165], v[178:181], v[42:45]
	v_mfma_f32_16x16x32_f16 v[30:33], v[154:157], v[186:189], v[30:33]
	v_mfma_f32_16x16x32_f16 v[26:29], v[162:165], v[186:189], v[26:29]
	v_mfma_f32_16x16x32_f16 v[14:17], v[154:157], v[194:197], v[14:17]
	v_mfma_f32_16x16x32_f16 v[10:13], v[162:165], v[194:197], v[10:13]
	v_mfma_f32_16x16x32_f16 v[54:57], v[198:201], v[166:169], v[54:57]
	v_mfma_f32_16x16x32_f16 v[50:53], v[220:223], v[166:169], v[50:53]
	v_mfma_f32_16x16x32_f16 v[38:41], v[198:201], v[174:177], v[38:41]
	v_mfma_f32_16x16x32_f16 v[34:37], v[220:223], v[174:177], v[34:37]
	v_mfma_f32_16x16x32_f16 v[22:25], v[198:201], v[182:185], v[22:25]
	v_mfma_f32_16x16x32_f16 v[18:21], v[220:223], v[182:185], v[18:21]
	v_mfma_f32_16x16x32_f16 v[6:9], v[198:201], v[190:193], v[6:9]
	v_mfma_f32_16x16x32_f16 v[2:5], v[220:223], v[190:193], v[2:5]
	v_mfma_f32_16x16x32_f16 v[54:57], v[202:205], v[170:173], v[54:57]
	v_mfma_f32_16x16x32_f16 v[50:53], v[224:227], v[170:173], v[50:53]
	v_mfma_f32_16x16x32_f16 v[38:41], v[202:205], v[178:181], v[38:41]
	v_mfma_f32_16x16x32_f16 v[34:37], v[224:227], v[178:181], v[34:37]
	v_mfma_f32_16x16x32_f16 v[22:25], v[202:205], v[186:189], v[22:25]
	v_mfma_f32_16x16x32_f16 v[18:21], v[224:227], v[186:189], v[18:21]
	v_mfma_f32_16x16x32_f16 v[6:9], v[202:205], v[194:197], v[6:9]
	v_mfma_f32_16x16x32_f16 v[2:5], v[224:227], v[194:197], v[2:5]
	s_barrier
	s_cbranch_scc1 .Lg4x_268

; #define PG8_STAGE(bufoff, gbase, voff) do { _Pragma("unroll") for (int _i = 0; _i < 2; ++_i) \
;         __builtin_amdgcn_global_load_lds((const unsigned*)((const char*)(gbase) + (voff)[_i]), (LAS unsigned*)(lds + (bufoff) + ldsw + _i * 8192), 16, 0, 0); } while (0)
; #define PG8_LDA(dst, b, h) do { _Pragma("unroll") for (int m = 0; m < 4; ++m) _Pragma("unroll") for (int k = 0; k < 2; ++k) dst[m][k] = *(const LAS h16x8*)(lds + PG8_SA(b, h) + aoff + m * 2048 + k * 1024); } while (0)
; #define PG8_LDB(dst, b, h) do { _Pragma("unroll") for (int n = 0; n < 2; ++n) _Pragma("unroll") for (int k = 0; k < 2; ++k) dst[n][k] = *(const LAS h16x8*)(lds + PG8_SB(b, h) + boff + n * 2048 + k * 1024); } while (0)
; #define PG8_MMA(ai, bj, At, Bt_) do { __builtin_amdgcn_s_setprio(1); _Pragma("unroll") for (int m = 0; m < 4; ++m) _Pragma("unroll") for (int n = 0; n < 2; ++n) _Pragma("unroll") for (int k = 0; k < 2; ++k) \
;         acc[ai][bj][m][n] = __builtin_amdgcn_mfma_f32_16x16x32_f16(Bt_[n][k], At[m][k], acc[ai][bj][m][n], 0, 0, 0); __builtin_amdgcn_s_setprio(0); } while (0)
; #define PG8_WAIT_V(n) asm volatile("s_waitcnt vmcnt(" #n ")" ::: "memory")
; #define PG8_WAIT_L(n) asm volatile("s_waitcnt lgkmcnt(" #n ")" ::: "memory")
; #define PG8_BAR __builtin_amdgcn_s_barrier()
; #define PG8_SCHED __builtin_amdgcn_sched_barrier(0)
; template <class Epi, class AMap>
; __device__ __forceinline__ void gemm_phase(LAS unsigned char* lds, const AMap am, const int lda, const h16* Bt, const int ldb, const int M, const int N, const int K, const Epi& E) {
;     ...
;             PG8_LDB(B0, 0, 0); PG8_SCHED; PG8_LDA(At, 0, 0); PG8_STAGE(PG8_SA(1, 1), a1 + hstepA, voffA);
;             PG8_WAIT_L(8); PG8_BAR; PG8_WAIT_L(0); PG8_MMA(0, 0, At, B0); PG8_BAR; PG8_SCHED;
;             PG8_LDB(B1, 0, 1); PG8_STAGE(PG8_SB(0, 0), b2, voffB);
;             PG8_BAR; PG8_WAIT_L(0); PG8_MMA(0, 1, At, B1); PG8_BAR;
;             PG8_LDA(At, 0, 1); PG8_STAGE(PG8_SA(0, 0), a2, voffA);
;             PG8_BAR; PG8_WAIT_L(0); PG8_MMA(1, 0, At, B0); PG8_BAR; PG8_SCHED;
;             PG8_STAGE(PG8_SB(0, 1), b2 + hstepB, voffB);
;             PG8_WAIT_V(6); PG8_BAR; PG8_MMA(1, 1, At, B1); PG8_BAR;
.Lg4p_799:
	s_add_u32 s40, s0, 0xfff80080
	s_addc_u32 s41, s1, -1
	s_add_i32 s45, 0, 0x10000
	v_add_u32_e32 v152, s45, v155
	ds_read_b128 v[130:133], v152
	ds_read_b128 v[134:137], v152 offset:1024
	ds_read_b128 v[148:151], v152 offset:2048
	ds_read_b128 v[158:161], v152 offset:3072
	s_cmp_eq_u32 s43, 28
	s_cselect_b32 s49, s47, s41
	s_cselect_b32 s48, s46, s40
	s_cselect_b32 s41, s29, s35
	s_cselect_b32 s40, s20, s21
	v_lshl_add_u64 v[152:153], s[0:1], 0, v[144:145]
	s_add_i32 m0, s23, 0xc000
	ds_read_b128 v[162:165], v157
	ds_read_b128 v[166:169], v157 offset:1024
	ds_read_b128 v[170:173], v157 offset:2048
	ds_read_b128 v[174:177], v157 offset:3072
	ds_read_b128 v[178:181], v157 offset:4096
	ds_read_b128 v[182:185], v157 offset:5120
	ds_read_b128 v[186:189], v157 offset:6144
	ds_read_b128 v[190:193], v157 offset:7168
	global_load_lds_dwordx4 v[152:153], off
	v_lshl_add_u64 v[152:153], s[0:1], 0, v[146:147]
	s_add_i32 m0, s23, 0xe000
	s_nop 0
	global_load_lds_dwordx4 v[152:153], off
	s_waitcnt lgkmcnt(11)
	s_add_i32 s60, 0, 0x14000
	v_add_u32_e32 v152, s60, v155
	s_add_i32 s45, s45, s72
	ds_read_b128 v[194:197], v152
	ds_read_b128 v[198:201], v152 offset:1024
	ds_read_b128 v[202:205], v152 offset:2048
	ds_read_b128 v[220:223], v152 offset:3072
	s_waitcnt vmcnt(24) lgkmcnt(0)
	s_barrier
	v_mfma_f32_16x16x32_f16 v[126:129], v[130:133], v[162:165], 0
	v_mfma_f32_16x16x32_f16 v[122:125], v[148:151], v[162:165], 0
	v_mfma_f32_16x16x32_f16 v[110:113], v[130:133], v[170:173], 0
	v_mfma_f32_16x16x32_f16 v[106:109], v[148:151], v[170:173], 0
	v_mfma_f32_16x16x32_f16 v[94:97], v[130:133], v[178:181], 0
	v_mfma_f32_16x16x32_f16 v[90:93], v[148:151], v[178:181], 0
	v_mfma_f32_16x16x32_f16 v[78:81], v[130:133], v[186:189], 0
	v_mfma_f32_16x16x32_f16 v[74:77], v[148:151], v[186:189], 0
	v_mfma_f32_16x16x32_f16 v[126:129], v[134:137], v[166:169], v[126:129]
	v_mfma_f32_16x16x32_f16 v[122:125], v[158:161], v[166:169], v[122:125]
	v_mfma_f32_16x16x32_f16 v[110:113], v[134:137], v[174:177], v[110:113]
	v_mfma_f32_16x16x32_f16 v[106:109], v[158:161], v[174:177], v[106:109]
	v_mfma_f32_16x16x32_f16 v[94:97], v[134:137], v[182:185], v[94:97]
	v_mfma_f32_16x16x32_f16 v[90:93], v[158:161], v[182:185], v[90:93]
	v_mfma_f32_16x16x32_f16 v[78:81], v[134:137], v[190:193], v[78:81]
	v_mfma_f32_16x16x32_f16 v[74:77], v[158:161], v[190:193], v[74:77]
	v_mfma_f32_16x16x32_f16 v[118:121], v[194:197], v[162:165], 0
	v_mfma_f32_16x16x32_f16 v[114:117], v[202:205], v[162:165], 0
	v_mfma_f32_16x16x32_f16 v[102:105], v[194:197], v[170:173], 0
	v_mfma_f32_16x16x32_f16 v[98:101], v[202:205], v[170:173], 0
	v_mfma_f32_16x16x32_f16 v[86:89], v[194:197], v[178:181], 0
	v_mfma_f32_16x16x32_f16 v[82:85], v[202:205], v[178:181], 0
	v_mfma_f32_16x16x32_f16 v[70:73], v[194:197], v[186:189], 0
	v_mfma_f32_16x16x32_f16 v[66:69], v[202:205], v[186:189], 0
	v_mfma_f32_16x16x32_f16 v[118:121], v[198:201], v[166:169], v[118:121]
	v_mfma_f32_16x16x32_f16 v[114:117], v[220:223], v[166:169], v[114:117]
	v_mfma_f32_16x16x32_f16 v[102:105], v[198:201], v[174:177], v[102:105]
	v_mfma_f32_16x16x32_f16 v[98:101], v[220:223], v[174:177], v[98:101]
	v_mfma_f32_16x16x32_f16 v[86:89], v[198:201], v[182:185], v[86:89]
	v_mfma_f32_16x16x32_f16 v[82:85], v[220:223], v[182:185], v[82:85]
	v_mfma_f32_16x16x32_f16 v[70:73], v[198:201], v[190:193], v[70:73]
	v_mfma_f32_16x16x32_f16 v[66:69], v[220:223], v[190:193], v[66:69]
	s_barrier
	v_lshl_add_u64 v[152:153], s[40:41], 0, v[0:1]
	s_mov_b32 m0, s45
	v_lshl_add_u64 v[206:207], s[40:41], 0, v[142:143]
	global_load_lds_dwordx4 v[152:153], off
	s_add_i32 m0, s45, 0x2000
	s_nop 0
	global_load_lds_dwordx4 v[206:207], off
	s_mov_b32 m0, s23
	v_lshl_add_u64 v[212:213], s[48:49], 0, v[138:139]
	ds_read_b128 v[162:165], v157 offset:16384
	ds_read_b128 v[166:169], v157 offset:17408
	ds_read_b128 v[170:173], v157 offset:18432
	ds_read_b128 v[174:177], v157 offset:19456
	ds_read_b128 v[178:181], v157 offset:20480
	ds_read_b128 v[182:185], v157 offset:21504
	ds_read_b128 v[186:189], v157 offset:22528
	ds_read_b128 v[190:193], v157 offset:23552
	global_load_lds_dwordx4 v[212:213], off
	v_lshl_add_u64 v[224:225], s[48:49], 0, v[140:141]
	s_mov_b32 m0, s27
	s_nop 0
	global_load_lds_dwordx4 v[224:225], off
	s_add_u32 s50, s40, 0x80000
	s_addc_u32 s51, s41, 0
	s_add_i32 s45, s60, s72
	v_lshl_add_u64 v[232:233], s[50:51], 0, v[0:1]
	s_mov_b32 m0, s45
	s_nop 0
	global_load_lds_dwordx4 v[232:233], off
	v_lshl_add_u64 v[232:233], s[50:51], 0, v[142:143]
	s_add_i32 m0, s45, 0x2000
	s_nop 0
	global_load_lds_dwordx4 v[232:233], off
	s_waitcnt vmcnt(8) lgkmcnt(0)
	s_barrier
; #define PG8_STAGE(bufoff, gbase, voff) do { _Pragma("unroll") for (int _i = 0; _i < 2; ++_i) \
;         __builtin_amdgcn_global_load_lds((const unsigned*)((const char*)(gbase) + (voff)[_i]), (LAS unsigned*)(lds + (bufoff) + ldsw + _i * 8192), 16, 0, 0); } while (0)
; #define PG8_LDA(dst, b, h) do { _Pragma("unroll") for (int m = 0; m < 4; ++m) _Pragma("unroll") for (int k = 0; k < 2; ++k) dst[m][k] = *(const LAS h16x8*)(lds + PG8_SA(b, h) + aoff + m * 2048 + k * 1024); } while (0)
; #define PG8_LDB(dst, b, h) do { _Pragma("unroll") for (int n = 0; n < 2; ++n) _Pragma("unroll") for (int k = 0; k < 2; ++k) dst[n][k] = *(const LAS h16x8*)(lds + PG8_SB(b, h) + boff + n * 2048 + k * 1024); } while (0)
; #define PG8_MMA(ai, bj, At, Bt_) do { __builtin_amdgcn_s_setprio(1); _Pragma("unroll") for (int m = 0; m < 4; ++m) _Pragma("unroll") for (int n = 0; n < 2; ++n) _Pragma("unroll") for (int k = 0; k < 2; ++k) \
;         acc[ai][bj][m][n] = __builtin_amdgcn_mfma_f32_16x16x32_f16(Bt_[n][k], At[m][k], acc[ai][bj][m][n], 0, 0, 0); __builtin_amdgcn_s_setprio(0); } while (0)
; #define PG8_WAIT_V(n) asm volatile("s_waitcnt vmcnt(" #n ")" ::: "memory")
; #define PG8_WAIT_L(n) asm volatile("s_waitcnt lgkmcnt(" #n ")" ::: "memory")
; #define PG8_BAR __builtin_amdgcn_s_barrier()
; #define PG8_SCHED __builtin_amdgcn_sched_barrier(0)
; template <class Epi, class AMap>
; __device__ __forceinline__ void gemm_phase(LAS unsigned char* lds, const AMap am, const int lda, const h16* Bt, const int ldb, const int M, const int N, const int K, const Epi& E) {
;     ...
;             PG8_WAIT_V(6); PG8_BAR; PG8_MMA(1, 1, At, B1); PG8_BAR;
;             PG8_LDB(B0, 1, 0); PG8_SCHED; PG8_LDA(At, 1, 0); PG8_STAGE(PG8_SA(0, 1), a2 + hstepA, voffA);
;             PG8_WAIT_L(8); PG8_BAR; PG8_WAIT_L(0); PG8_MMA(0, 0, At, B0); PG8_BAR; PG8_SCHED;
;             PG8_LDB(B1, 1, 1); PG8_STAGE(PG8_SB(1, 0), b3, voffB);
;             PG8_BAR; PG8_WAIT_L(0); PG8_MMA(0, 1, At, B1); PG8_BAR;
	v_mfma_f32_16x16x32_f16 v[62:65], v[130:133], v[162:165], 0
	v_mfma_f32_16x16x32_f16 v[58:61], v[148:151], v[162:165], 0
	v_mfma_f32_16x16x32_f16 v[46:49], v[130:133], v[170:173], 0
	v_mfma_f32_16x16x32_f16 v[42:45], v[148:151], v[170:173], 0
	v_mfma_f32_16x16x32_f16 v[30:33], v[130:133], v[178:181], 0
	v_mfma_f32_16x16x32_f16 v[26:29], v[148:151], v[178:181], 0
	v_mfma_f32_16x16x32_f16 v[14:17], v[130:133], v[186:189], 0
	v_mfma_f32_16x16x32_f16 v[10:13], v[148:151], v[186:189], 0
	v_mfma_f32_16x16x32_f16 v[62:65], v[134:137], v[166:169], v[62:65]
	v_mfma_f32_16x16x32_f16 v[58:61], v[158:161], v[166:169], v[58:61]
	v_mfma_f32_16x16x32_f16 v[46:49], v[134:137], v[174:177], v[46:49]
	v_mfma_f32_16x16x32_f16 v[42:45], v[158:161], v[174:177], v[42:45]
	v_mfma_f32_16x16x32_f16 v[30:33], v[134:137], v[182:185], v[30:33]
	v_mfma_f32_16x16x32_f16 v[26:29], v[158:161], v[182:185], v[26:29]
	v_mfma_f32_16x16x32_f16 v[14:17], v[134:137], v[190:193], v[14:17]
	v_mfma_f32_16x16x32_f16 v[10:13], v[158:161], v[190:193], v[10:13]
	v_mfma_f32_16x16x32_f16 v[54:57], v[194:197], v[162:165], 0
	v_mfma_f32_16x16x32_f16 v[50:53], v[202:205], v[162:165], 0
	v_mfma_f32_16x16x32_f16 v[38:41], v[194:197], v[170:173], 0
	v_mfma_f32_16x16x32_f16 v[34:37], v[202:205], v[170:173], 0
	v_mfma_f32_16x16x32_f16 v[22:25], v[194:197], v[178:181], 0
	v_mfma_f32_16x16x32_f16 v[18:21], v[202:205], v[178:181], 0
	v_mfma_f32_16x16x32_f16 v[6:9], v[194:197], v[186:189], 0
	v_mfma_f32_16x16x32_f16 v[2:5], v[202:205], v[186:189], 0
	v_mfma_f32_16x16x32_f16 v[54:57], v[198:201], v[166:169], v[54:57]
	v_mfma_f32_16x16x32_f16 v[50:53], v[220:223], v[166:169], v[50:53]
	v_mfma_f32_16x16x32_f16 v[38:41], v[198:201], v[174:177], v[38:41]
	v_mfma_f32_16x16x32_f16 v[34:37], v[220:223], v[174:177], v[34:37]
	v_mfma_f32_16x16x32_f16 v[22:25], v[198:201], v[182:185], v[22:25]
	v_mfma_f32_16x16x32_f16 v[18:21], v[220:223], v[182:185], v[18:21]
	v_mfma_f32_16x16x32_f16 v[6:9], v[198:201], v[190:193], v[6:9]
	v_mfma_f32_16x16x32_f16 v[2:5], v[220:223], v[190:193], v[2:5]
	s_barrier
	s_add_i32 s45, 0, 0x18000
	v_add_u32_e32 v234, s45, v155
	ds_read_b128 v[130:133], v234
	ds_read_b128 v[134:137], v234 offset:1024
	ds_read_b128 v[148:151], v234 offset:2048
	ds_read_b128 v[158:161], v234 offset:3072
	s_add_u32 s48, s48, 0x80000
	s_addc_u32 s49, s49, 0
	s_mov_b32 m0, s73
	v_lshl_add_u64 v[232:233], s[48:49], 0, v[138:139]
	ds_read_b128 v[162:165], v157 offset:32768
	ds_read_b128 v[166:169], v157 offset:33792
	ds_read_b128 v[170:173], v157 offset:34816
	ds_read_b128 v[174:177], v157 offset:35840
	ds_read_b128 v[178:181], v157 offset:36864
	ds_read_b128 v[182:185], v157 offset:37888
	ds_read_b128 v[186:189], v157 offset:38912
	ds_read_b128 v[190:193], v157 offset:39936
	global_load_lds_dwordx4 v[232:233], off
	v_lshl_add_u64 v[232:233], s[48:49], 0, v[140:141]
	s_mov_b32 m0, s74
	s_nop 0
	global_load_lds_dwordx4 v[232:233], off
	s_waitcnt lgkmcnt(11)
	s_add_i32 s48, 0, 0x1c000
	s_add_i32 s45, s45, s72
	v_add_u32_e32 v214, s48, v155
	v_lshl_add_u64 v[152:153], v[152:153], 0, s[92:93]
	s_mov_b32 m0, s45
	ds_read_b128 v[194:197], v214
	ds_read_b128 v[198:201], v214 offset:1024
	ds_read_b128 v[202:205], v214 offset:2048
	ds_read_b128 v[220:223], v214 offset:3072
	s_waitcnt vmcnt(8) lgkmcnt(0)
	s_barrier
	v_mfma_f32_16x16x32_f16 v[126:129], v[130:133], v[162:165], v[126:129]
	v_mfma_f32_16x16x32_f16 v[122:125], v[148:151], v[162:165], v[122:125]
	v_mfma_f32_16x16x32_f16 v[110:113], v[130:133], v[170:173], v[110:113]
	v_mfma_f32_16x16x32_f16 v[106:109], v[148:151], v[170:173], v[106:109]
	v_mfma_f32_16x16x32_f16 v[94:97], v[130:133], v[178:181], v[94:97]
	v_mfma_f32_16x16x32_f16 v[90:93], v[148:151], v[178:181], v[90:93]
	v_mfma_f32_16x16x32_f16 v[78:81], v[130:133], v[186:189], v[78:81]
	v_mfma_f32_16x16x32_f16 v[74:77], v[148:151], v[186:189], v[74:77]
	v_mfma_f32_16x16x32_f16 v[126:129], v[134:137], v[166:169], v[126:129]
	v_mfma_f32_16x16x32_f16 v[122:125], v[158:161], v[166:169], v[122:125]
	v_mfma_f32_16x16x32_f16 v[110:113], v[134:137], v[174:177], v[110:113]
	v_mfma_f32_16x16x32_f16 v[106:109], v[158:161], v[174:177], v[106:109]
	v_mfma_f32_16x16x32_f16 v[94:97], v[134:137], v[182:185], v[94:97]
	v_mfma_f32_16x16x32_f16 v[90:93], v[158:161], v[182:185], v[90:93]
	v_mfma_f32_16x16x32_f16 v[78:81], v[134:137], v[190:193], v[78:81]
	v_mfma_f32_16x16x32_f16 v[74:77], v[158:161], v[190:193], v[74:77]
	v_mfma_f32_16x16x32_f16 v[118:121], v[194:197], v[162:165], v[118:121]
	v_mfma_f32_16x16x32_f16 v[114:117], v[202:205], v[162:165], v[114:117]
	v_mfma_f32_16x16x32_f16 v[102:105], v[194:197], v[170:173], v[102:105]
	v_mfma_f32_16x16x32_f16 v[98:101], v[202:205], v[170:173], v[98:101]
	v_mfma_f32_16x16x32_f16 v[86:89], v[194:197], v[178:181], v[86:89]
	v_mfma_f32_16x16x32_f16 v[82:85], v[202:205], v[178:181], v[82:85]
	v_mfma_f32_16x16x32_f16 v[70:73], v[194:197], v[186:189], v[70:73]
	v_mfma_f32_16x16x32_f16 v[66:69], v[202:205], v[186:189], v[66:69]
	v_mfma_f32_16x16x32_f16 v[118:121], v[198:201], v[166:169], v[118:121]
	v_mfma_f32_16x16x32_f16 v[114:117], v[220:223], v[166:169], v[114:117]
	v_mfma_f32_16x16x32_f16 v[102:105], v[198:201], v[174:177], v[102:105]
	v_mfma_f32_16x16x32_f16 v[98:101], v[220:223], v[174:177], v[98:101]
	v_mfma_f32_16x16x32_f16 v[86:89], v[198:201], v[182:185], v[86:89]
	v_mfma_f32_16x16x32_f16 v[82:85], v[220:223], v[182:185], v[82:85]
	v_mfma_f32_16x16x32_f16 v[70:73], v[198:201], v[190:193], v[70:73]
	v_mfma_f32_16x16x32_f16 v[66:69], v[220:223], v[190:193], v[66:69]
	s_barrier
; #define PG8_STAGE(bufoff, gbase, voff) do { _Pragma("unroll") for (int _i = 0; _i < 2; ++_i) \
;         __builtin_amdgcn_global_load_lds((const unsigned*)((const char*)(gbase) + (voff)[_i]), (LAS unsigned*)(lds + (bufoff) + ldsw + _i * 8192), 16, 0, 0); } while (0)
; #define PG8_LDA(dst, b, h) do { _Pragma("unroll") for (int m = 0; m < 4; ++m) _Pragma("unroll") for (int k = 0; k < 2; ++k) dst[m][k] = *(const LAS h16x8*)(lds + PG8_SA(b, h) + aoff + m * 2048 + k * 1024); } while (0)
; #define PG8_MMA(ai, bj, At, Bt_) do { __builtin_amdgcn_s_setprio(1); _Pragma("unroll") for (int m = 0; m < 4; ++m) _Pragma("unroll") for (int n = 0; n < 2; ++n) _Pragma("unroll") for (int k = 0; k < 2; ++k) \
;         acc[ai][bj][m][n] = __builtin_amdgcn_mfma_f32_16x16x32_f16(Bt_[n][k], At[m][k], acc[ai][bj][m][n], 0, 0, 0); __builtin_amdgcn_s_setprio(0); } while (0)
; #define PG8_WAIT_V(n) asm volatile("s_waitcnt vmcnt(" #n ")" ::: "memory")
; #define PG8_WAIT_L(n) asm volatile("s_waitcnt lgkmcnt(" #n ")" ::: "memory")
; #define PG8_BAR __builtin_amdgcn_s_barrier()
; #define PG8_SCHED __builtin_amdgcn_sched_barrier(0)
; template <class Epi, class AMap>
; __device__ __forceinline__ void gemm_phase(LAS unsigned char* lds, const AMap am, const int lda, const h16* Bt, const int ldb, const int M, const int N, const int K, const Epi& E) {
;     ...
;             PG8_LDA(At, 1, 1); PG8_STAGE(PG8_SA(1, 0), a3, voffA);
;             PG8_BAR; PG8_WAIT_L(0); PG8_MMA(1, 0, At, B0); PG8_BAR; PG8_SCHED;
;             PG8_STAGE(PG8_SB(1, 1), b3 + hstepB, voffB);
;             PG8_WAIT_V(6); PG8_BAR; PG8_MMA(1, 1, At, B1); PG8_BAR;
	global_load_lds_dwordx4 v[152:153], off
	v_lshl_add_u64 v[152:153], v[206:207], 0, s[92:93]
	s_add_i32 m0, s45, 0x2000
	s_nop 0
	global_load_lds_dwordx4 v[152:153], off
	s_mov_b32 m0, s75
	v_lshl_add_u64 v[152:153], v[212:213], 0, s[92:93]
	ds_read_b128 v[162:165], v157 offset:49152
	ds_read_b128 v[166:169], v157 offset:50176
	ds_read_b128 v[170:173], v157 offset:51200
	ds_read_b128 v[174:177], v157 offset:52224
	ds_read_b128 v[178:181], v157 offset:53248
	ds_read_b128 v[182:185], v157 offset:54272
	ds_read_b128 v[186:189], v157 offset:55296
	ds_read_b128 v[190:193], v157 offset:56320
	global_load_lds_dwordx4 v[152:153], off
	v_lshl_add_u64 v[152:153], v[224:225], 0, s[92:93]
	s_mov_b32 m0, s76
	s_nop 0
	global_load_lds_dwordx4 v[152:153], off
	s_add_u32 s40, s40, 0x80080
	s_addc_u32 s41, s41, 0
	s_add_i32 s45, s48, s72
	v_lshl_add_u64 v[232:233], s[40:41], 0, v[0:1]
	s_mov_b32 m0, s45
	s_nop 0
	global_load_lds_dwordx4 v[232:233], off
	v_lshl_add_u64 v[232:233], s[40:41], 0, v[142:143]
	s_add_i32 m0, s45, 0x2000
	s_nop 0
	global_load_lds_dwordx4 v[232:233], off
	s_add_i32 s43, s43, 2
	s_add_u32 s0, s0, 0x100
	s_addc_u32 s1, s1, 0
	s_add_u32 s21, s21, 0x100
	s_addc_u32 s35, s35, 0
	s_cmp_gt_u32 s43, 29
	s_waitcnt vmcnt(8) lgkmcnt(0)
	s_barrier
	v_mfma_f32_16x16x32_f16 v[62:65], v[130:133], v[162:165], v[62:65]
	v_mfma_f32_16x16x32_f16 v[58:61], v[148:151], v[162:165], v[58:61]
	v_mfma_f32_16x16x32_f16 v[46:49], v[130:133], v[170:173], v[46:49]
	v_mfma_f32_16x16x32_f16 v[42:45], v[148:151], v[170:173], v[42:45]
	v_mfma_f32_16x16x32_f16 v[30:33], v[130:133], v[178:181], v[30:33]
	v_mfma_f32_16x16x32_f16 v[26:29], v[148:151], v[178:181], v[26:29]
	v_mfma_f32_16x16x32_f16 v[14:17], v[130:133], v[186:189], v[14:17]
	v_mfma_f32_16x16x32_f16 v[10:13], v[148:151], v[186:189], v[10:13]
	v_mfma_f32_16x16x32_f16 v[62:65], v[134:137], v[166:169], v[62:65]
	v_mfma_f32_16x16x32_f16 v[58:61], v[158:161], v[166:169], v[58:61]
	v_mfma_f32_16x16x32_f16 v[46:49], v[134:137], v[174:177], v[46:49]
	v_mfma_f32_16x16x32_f16 v[42:45], v[158:161], v[174:177], v[42:45]
	v_mfma_f32_16x16x32_f16 v[30:33], v[134:137], v[182:185], v[30:33]
	v_mfma_f32_16x16x32_f16 v[26:29], v[158:161], v[182:185], v[26:29]
	v_mfma_f32_16x16x32_f16 v[14:17], v[134:137], v[190:193], v[14:17]
	v_mfma_f32_16x16x32_f16 v[10:13], v[158:161], v[190:193], v[10:13]
	v_mfma_f32_16x16x32_f16 v[54:57], v[194:197], v[162:165], v[54:57]
	v_mfma_f32_16x16x32_f16 v[50:53], v[202:205], v[162:165], v[50:53]
	v_mfma_f32_16x16x32_f16 v[38:41], v[194:197], v[170:173], v[38:41]
	v_mfma_f32_16x16x32_f16 v[34:37], v[202:205], v[170:173], v[34:37]
	v_mfma_f32_16x16x32_f16 v[22:25], v[194:197], v[178:181], v[22:25]
	v_mfma_f32_16x16x32_f16 v[18:21], v[202:205], v[178:181], v[18:21]
	v_mfma_f32_16x16x32_f16 v[6:9], v[194:197], v[186:189], v[6:9]
	v_mfma_f32_16x16x32_f16 v[2:5], v[202:205], v[186:189], v[2:5]
	v_mfma_f32_16x16x32_f16 v[54:57], v[198:201], v[166:169], v[54:57]
	v_mfma_f32_16x16x32_f16 v[50:53], v[220:223], v[166:169], v[50:53]
	v_mfma_f32_16x16x32_f16 v[38:41], v[198:201], v[174:177], v[38:41]
	v_mfma_f32_16x16x32_f16 v[34:37], v[220:223], v[174:177], v[34:37]
	v_mfma_f32_16x16x32_f16 v[22:25], v[198:201], v[182:185], v[22:25]
	v_mfma_f32_16x16x32_f16 v[18:21], v[220:223], v[182:185], v[18:21]
	v_mfma_f32_16x16x32_f16 v[6:9], v[198:201], v[190:193], v[6:9]
	v_mfma_f32_16x16x32_f16 v[2:5], v[220:223], v[190:193], v[2:5]
	s_barrier
	s_cbranch_scc1 .Lg4x_799
